# WFD: P0 heavy chunk - all 92 ds_bpermute lane exchanges (wave_sum + head butterfly) replaced by DPP (xor 1/2/4/8) and permlane16/32_swap + select (xor 16/32)
# baseline (speedup 1.0000x reference)
; __device__ __forceinline__ void p0_phase(const Args& a, LAS unsigned char* lds, int tid, int lane, int wave) {
;     ...
; #pragma unroll
;                 for (int u = 0; u < 4; ++u) { const int row = c * 64 + wave * 8 + i4 * 4 + u; const float* xrow = row < MP ? a.in[0] + (size_t)row * D : a.in[1] + (size_t)(row - MP) * D;
; #pragma unroll
;                     for (int j = 0; j < 16; ++j) xa[u][j] = xrow[lane + 64 * j]; }
; #pragma unroll
;                 for (int u = 0; u < 4; ++u) {
;                 const int rl = wave * 8 + i4 * 4 + u, row = c * 64 + rl;
;                 float ss = 0.f;
; #pragma unroll
;                 for (int j = 0; j < 16; ++j) ss += xa[u][j] * xa[u][j];
;                 const float rstd = 1.0f / sqrtf(wave_sum(ss) * (1.f / D) + EPS);
.LBB0_33:
	s_or_b32 s11, s10, s66
	s_add_i32 s0, s11, 0xffffc000
	s_ashr_i32 s1, s11, 31
	s_cmpk_lt_i32 s11, 0x4000
	s_cselect_b32 s1, s1, 0
	s_cselect_b32 s0, s11, s0
	s_cselect_b32 s12, s53, s55
	s_cselect_b32 s13, s52, s54
	s_lshl_b64 s[0:1], s[0:1], 12
	s_add_u32 s0, s13, s0
	s_addc_u32 s1, s12, s1
	global_load_dword v126, v59, s[0:1] offset:256
	global_load_dword v147, v59, s[0:1] offset:512
	global_load_dword v146, v59, s[0:1] offset:768
	global_load_dword v145, v59, s[0:1] offset:1024
	global_load_dword v144, v59, s[0:1] offset:1280
	global_load_dword v143, v59, s[0:1] offset:1536
	global_load_dword v142, v59, s[0:1] offset:1792
	global_load_dword v0, v59, s[0:1]
	global_load_dword v141, v59, s[0:1] offset:2048
	global_load_dword v127, v59, s[0:1] offset:2304
	global_load_dword v120, v59, s[0:1] offset:2560
	global_load_dword v119, v59, s[0:1] offset:2816
	global_load_dword v118, v59, s[0:1] offset:3072
	global_load_dword v117, v59, s[0:1] offset:3328
	global_load_dword v116, v59, s[0:1] offset:3584
	global_load_dword v33, v58, s[0:1]
	s_or_b32 s0, s11, 1
	s_add_i32 s12, s11, 0xffffc001
	s_ashr_i32 s1, s0, 31
	s_cmpk_lt_i32 s0, 0x4000
	s_cselect_b32 s1, s1, 0
	s_cselect_b32 s0, s0, s12
	s_cselect_b32 s12, s53, s55
	s_cselect_b32 s13, s52, s54
	s_lshl_b64 s[0:1], s[0:1], 12
	s_add_u32 vcc_lo, s13, s0
	s_addc_u32 vcc_hi, s12, s1
	s_or_b32 s0, s11, 2
	s_add_i32 s12, s11, 0xffffc002
	s_ashr_i32 s1, s0, 31
	s_cmpk_lt_i32 s0, 0x4000
	s_cselect_b32 s1, s1, 0
	s_cselect_b32 s0, s0, s12
	s_cselect_b32 s12, s53, s55
	s_cselect_b32 s13, s52, s54
	s_lshl_b64 s[0:1], s[0:1], 12
	s_add_u32 s0, s13, s0
	s_addc_u32 s1, s12, s1
	s_or_b32 s12, s11, 3
	s_addk_i32 s11, 0xc003
	s_ashr_i32 s13, s12, 31
	s_cmpk_lt_i32 s12, 0x4000
	s_cselect_b32 s93, s13, 0
	s_cselect_b32 s92, s12, s11
	s_cselect_b32 s11, s53, s55
	s_cselect_b32 s12, s52, s54
	s_lshl_b64 s[92:93], s[92:93], 12
	s_add_u32 s92, s12, s92
	global_load_dword v111, v59, vcc
	s_addc_u32 s93, s11, s93
	global_load_dword v100, v58, vcc
	global_load_dword v84, v58, s[0:1]
	global_load_dword v20, v58, s[92:93]
	global_load_dword v115, v59, vcc offset:256
	global_load_dword v114, v59, vcc offset:512
	global_load_dword v113, v59, vcc offset:768
	global_load_dword v112, v59, vcc offset:1024
	global_load_dword v110, v59, vcc offset:1280
	global_load_dword v109, v59, vcc offset:1536
	global_load_dword v108, v59, vcc offset:1792
	global_load_dword v107, v59, vcc offset:2048
	global_load_dword v106, v59, vcc offset:2304
	global_load_dword v105, v59, vcc offset:2560
	global_load_dword v104, v59, vcc offset:2816
	global_load_dword v103, v59, vcc offset:3072
	global_load_dword v102, v59, vcc offset:3328
	global_load_dword v101, v59, vcc offset:3584
	global_load_dword v99, v59, s[0:1]
	global_load_dword v98, v59, s[0:1] offset:256
	global_load_dword v97, v59, s[0:1] offset:512
	global_load_dword v96, v59, s[0:1] offset:768
	global_load_dword v95, v59, s[0:1] offset:1024
	global_load_dword v94, v59, s[0:1] offset:1280
	global_load_dword v93, v59, s[0:1] offset:1536
	global_load_dword v92, v59, s[0:1] offset:1792
	global_load_dword v91, v59, s[0:1] offset:2048
	global_load_dword v90, v59, s[0:1] offset:2304
	global_load_dword v89, v59, s[0:1] offset:2560
	global_load_dword v88, v59, s[0:1] offset:2816
	global_load_dword v87, v59, s[0:1] offset:3072
	global_load_dword v86, v59, s[0:1] offset:3328
	global_load_dword v85, v59, s[0:1] offset:3584
	global_load_dword v82, v59, s[92:93]
	global_load_dword v81, v59, s[92:93] offset:256
	global_load_dword v80, v59, s[92:93] offset:512
	s_or_b32 s10, s10, s48
	s_waitcnt vmcnt(51)
	v_mul_f32_e32 v1, v126, v126
	s_waitcnt vmcnt(44)
	v_fmac_f32_e32 v1, v0, v0
	v_fmac_f32_e32 v1, v147, v147
	v_fmac_f32_e32 v1, v146, v146
	v_fmac_f32_e32 v1, v145, v145
	v_fmac_f32_e32 v1, v144, v144
	v_fmac_f32_e32 v1, v143, v143
	v_fmac_f32_e32 v1, v142, v142
	s_waitcnt vmcnt(43)
	v_fmac_f32_e32 v1, v141, v141
	s_waitcnt vmcnt(42)
	v_fmac_f32_e32 v1, v127, v127
	s_waitcnt vmcnt(41)
	v_fmac_f32_e32 v1, v120, v120
	s_waitcnt vmcnt(40)
	v_fmac_f32_e32 v1, v119, v119
	s_waitcnt vmcnt(39)
	v_fmac_f32_e32 v1, v118, v118
	s_waitcnt vmcnt(38)
	v_fmac_f32_e32 v1, v117, v117
	s_waitcnt vmcnt(37)
	v_fmac_f32_e32 v1, v116, v116
	s_waitcnt vmcnt(36)
	v_fmac_f32_e32 v1, v33, v33
	s_waitcnt lgkmcnt(0)
	s_nop 1
	v_mov_b32_dpp v21, v1 quad_perm:[1,0,3,2] row_mask:0xf bank_mask:0xf
	s_waitcnt lgkmcnt(0)
	v_add_f32_e32 v1, v1, v21
	s_nop 1
	v_mov_b32_dpp v21, v1 quad_perm:[2,3,0,1] row_mask:0xf bank_mask:0xf
	s_waitcnt lgkmcnt(0)
	v_add_f32_e32 v1, v1, v21
	s_nop 1
	v_mov_b32_dpp v21, v1 row_shl:4 row_mask:0xf bank_mask:0x5
	s_nop 1
	v_mov_b32_dpp v21, v1 row_shr:4 row_mask:0xf bank_mask:0xa
	s_waitcnt lgkmcnt(0)
	v_add_f32_e32 v1, v1, v21
	s_nop 1
	v_mov_b32_dpp v21, v1 row_ror:8 row_mask:0xf bank_mask:0xf
	s_waitcnt lgkmcnt(0)
	v_add_f32_e32 v1, v1, v21
	v_mov_b32_e32 v21, v1
	v_mov_b32_e32 v253, v1
	s_nop 1
	v_permlane16_swap_b32_e32 v21, v253
	v_cndmask_b32_e64 v21, v21, v253, s[28:29]
	s_waitcnt lgkmcnt(0)
	v_add_f32_e32 v1, v1, v21
	v_mov_b32_e32 v21, v1
	v_mov_b32_e32 v253, v1
	s_nop 1
	v_permlane32_swap_b32_e32 v21, v253
	v_cndmask_b32_e64 v21, v21, v253, s[26:27]
	s_waitcnt lgkmcnt(0)
; #define LAS __attribute__((address_space(3)))
; __device__ __forceinline__ unsigned cvt_pk_bf16(float lo, float hi) { unsigned r; asm volatile("v_cvt_pk_bf16_f32 %0, %1, %2" : "=v"(r) : "v"(lo), "v"(hi)); return r; }
; __device__ __forceinline__ void p0_phase(const Args& a, LAS unsigned char* lds, int tid, int lane, int wave) {
;     ...
;                 const float rstd = 1.0f / sqrtf(wave_sum(ss) * (1.f / D) + EPS);
;                 float f[16];
; #pragma unroll
;                 for (int h = 0; h < 16; ++h) f[h] = 0.f;
; #pragma unroll
;                 for (int j = 0; j < 16; ++j) { const float xn = xa[u][j] * rstd * gm[j];
;                     XN[(size_t)row * D + lane + 64 * j] = (bf16_t)(cvt_pk_bf16(xn, 0.f) & 0xffffu);
;                     const LAS f32x4* wp = (const LAS f32x4*)(wfl + (lane + 64 * j) * 16);
; #pragma unroll
;                     for (int q = 0; q < 4; ++q) { const f32x4 w = wp[q]; f[4 * q + 0] += xn * w[0]; f[4 * q + 1] += xn * w[1]; f[4 * q + 2] += xn * w[2]; f[4 * q + 3] += xn * w[3]; } }
	v_add_f32_e32 v1, v1, v21
	v_fmamk_f32 v1, v1, 0x3a800000, v60
	v_mul_f32_e32 v21, 0x4f800000, v1
	v_cmp_gt_f32_e32 vcc, s49, v1
	s_nop 1
	v_cndmask_b32_e32 v1, v1, v21, vcc
	v_sqrt_f32_e32 v21, v1
	s_nop 0
	v_add_u32_e32 v22, -1, v21
	v_add_u32_e32 v23, 1, v21
	v_fma_f32 v24, -v22, v21, v1
	v_fma_f32 v25, -v23, v21, v1
	v_cmp_ge_f32_e64 s[0:1], 0, v24
	s_nop 1
	v_cndmask_b32_e64 v21, v21, v22, s[0:1]
	v_cmp_lt_f32_e64 s[0:1], 0, v25
	global_load_dword v32, v59, s[92:93] offset:768
	global_load_dword v31, v59, s[92:93] offset:1024
	global_load_dword v30, v59, s[92:93] offset:1280
	global_load_dword v29, v59, s[92:93] offset:1536
	global_load_dword v28, v59, s[92:93] offset:1792
	global_load_dword v27, v59, s[92:93] offset:2048
	global_load_dword v26, v59, s[92:93] offset:2304
	global_load_dword v25, v59, s[92:93] offset:2560
	v_cndmask_b32_e64 v21, v21, v23, s[0:1]
	v_mul_f32_e32 v22, 0x37800000, v21
	v_cndmask_b32_e32 v21, v21, v22, vcc
	v_cmp_class_f32_e32 vcc, v1, v61
	s_nop 1
	v_cndmask_b32_e32 v1, v21, v1, vcc
	v_div_scale_f32 v21, s[0:1], v1, v1, 1.0
	v_rcp_f32_e32 v22, v21
	v_div_scale_f32 v23, vcc, 1.0, v1, 1.0
	s_add_i32 s0, s10, s45
	v_fma_f32 v24, -v21, v22, 1.0
	v_fmac_f32_e32 v22, v24, v22
	v_mul_f32_e32 v24, v23, v22
	v_fma_f32 v83, -v21, v24, v23
	v_fmac_f32_e32 v24, v83, v22
	v_fma_f32 v21, -v21, v24, v23
	v_div_fmas_f32 v21, v21, v22, v24
	v_div_fixup_f32 v139, v21, v1, 1.0
	v_mul_f32_e32 v0, v0, v139
	v_add_u32_e32 v83, s51, v57
	v_mul_f32_e32 v156, v9, v0
	global_load_dword v24, v59, s[92:93] offset:2816
	global_load_dword v23, v59, s[92:93] offset:3072
	global_load_dword v22, v59, s[92:93] offset:3328
	global_load_dword v21, v59, s[92:93] offset:3584
	v_cvt_pk_bf16_f32 v131, v156, v5
	s_ashr_i32 s1, s0, 31
	s_lshl_b64 s[92:93], s[0:1], 11
	s_waitcnt lgkmcnt(0)
	v_fma_f32 v135, v160, v156, 0
	v_fma_f32 v130, v161, v156, 0
	v_fma_f32 v129, v162, v156, 0
	s_waitcnt lgkmcnt(0)
	v_fma_f32 v122, v164, v156, 0
	v_fma_f32 v124, v165, v156, 0
	v_fma_f32 v123, v166, v156, 0
	v_fma_f32 v121, v167, v156, 0
	v_lshl_add_u64 v[0:1], v[6:7], 0, s[92:93]
	v_mul_f32_e32 v126, v126, v139
	s_waitcnt lgkmcnt(0)
	v_fma_f32 v140, v168, v156, 0
	v_fma_f32 v138, v169, v156, 0
	v_fma_f32 v137, v170, v156, 0
	v_fma_f32 v133, v171, v156, 0
	s_waitcnt lgkmcnt(0)
	v_fma_f32 v128, v156, v172, 0
	global_store_short v[0:1], v131, off
	v_mul_f32_e32 v157, v34, v126
	v_cvt_pk_bf16_f32 v158, v157, v5
	v_fma_f32 v136, v156, v173, 0
	v_fma_f32 v131, v156, v174, 0
	v_fma_f32 v126, v156, v175, 0
	v_fma_f32 v125, v163, v156, 0
	s_waitcnt lgkmcnt(0)
	v_fmac_f32_e32 v135, v157, v176
	v_fmac_f32_e32 v130, v157, v177
	v_fmac_f32_e32 v129, v157, v178
	v_fmac_f32_e32 v125, v157, v179
	s_waitcnt lgkmcnt(0)
	v_fmac_f32_e32 v122, v157, v180
	v_fmac_f32_e32 v124, v157, v181
	v_fmac_f32_e32 v123, v157, v182
	v_fmac_f32_e32 v121, v157, v183
	v_mul_f32_e32 v147, v147, v139
	s_waitcnt lgkmcnt(0)
	v_fmac_f32_e32 v140, v157, v184
	v_fmac_f32_e32 v138, v157, v185
	v_fmac_f32_e32 v137, v157, v186
	v_fmac_f32_e32 v133, v157, v187
	s_waitcnt lgkmcnt(0)
	v_fmac_f32_e32 v128, v157, v188
	global_store_short v[0:1], v158, off offset:128
	v_mul_f32_e32 v147, v35, v147
	v_cvt_pk_bf16_f32 v156, v147, v5
	v_fmac_f32_e32 v136, v157, v189
	v_fmac_f32_e32 v131, v157, v190
	v_fmac_f32_e32 v126, v157, v191
	s_waitcnt lgkmcnt(0)
	v_fmac_f32_e32 v135, v147, v192
	v_fmac_f32_e32 v130, v147, v193
	v_fmac_f32_e32 v129, v147, v194
	v_fmac_f32_e32 v125, v147, v195
	s_waitcnt lgkmcnt(0)
	v_fmac_f32_e32 v122, v147, v196
	v_fmac_f32_e32 v124, v147, v197
	v_fmac_f32_e32 v123, v147, v198
	v_fmac_f32_e32 v121, v147, v199
	v_mul_f32_e32 v146, v146, v139
	s_waitcnt lgkmcnt(0)
	v_fmac_f32_e32 v140, v147, v200
	v_fmac_f32_e32 v138, v147, v201
	v_fmac_f32_e32 v137, v147, v202
	v_fmac_f32_e32 v133, v147, v203
	s_waitcnt lgkmcnt(0)
	v_fmac_f32_e32 v128, v147, v204
	global_store_short v[0:1], v156, off offset:256
	v_mul_f32_e32 v156, v36, v146
	v_cvt_pk_bf16_f32 v157, v156, v5
	v_fmac_f32_e32 v136, v147, v205
	v_fmac_f32_e32 v131, v147, v206
	v_fmac_f32_e32 v126, v147, v207
	s_waitcnt lgkmcnt(0)
	v_fmac_f32_e32 v135, v156, v208
	v_fmac_f32_e32 v130, v156, v209
	v_mul_f32_e32 v145, v145, v139
	s_waitcnt lgkmcnt(0)
	v_fmac_f32_e32 v122, v156, v212
	v_fmac_f32_e32 v124, v156, v213
	v_fmac_f32_e32 v123, v156, v214
	v_fmac_f32_e32 v121, v156, v215
	v_fmac_f32_e32 v129, v156, v210
	s_waitcnt lgkmcnt(0)
	v_fmac_f32_e32 v140, v156, v216
	v_fmac_f32_e32 v138, v156, v217
	v_fmac_f32_e32 v137, v156, v218
	v_fmac_f32_e32 v133, v156, v219
	s_waitcnt lgkmcnt(0)
	v_fmac_f32_e32 v128, v156, v220
	global_store_short v[0:1], v157, off offset:384
	v_mul_f32_e32 v145, v37, v145
	v_cvt_pk_bf16_f32 v154, v145, v5
	v_fmac_f32_e32 v136, v156, v221
	v_fmac_f32_e32 v131, v156, v222
	v_fmac_f32_e32 v126, v156, v223
	v_fmac_f32_e32 v125, v156, v211
	s_waitcnt lgkmcnt(0)
	v_fmac_f32_e32 v135, v145, v224
	v_fmac_f32_e32 v130, v145, v225
	v_fmac_f32_e32 v129, v145, v226
	v_fmac_f32_e32 v125, v145, v227
	s_waitcnt lgkmcnt(0)
	v_fmac_f32_e32 v122, v145, v228
	v_fmac_f32_e32 v124, v145, v229
	v_fmac_f32_e32 v123, v145, v230
	v_fmac_f32_e32 v121, v145, v231
	v_mul_f32_e32 v144, v144, v139
	s_waitcnt lgkmcnt(0)
	v_fmac_f32_e32 v140, v145, v232
	v_fmac_f32_e32 v138, v145, v233
	v_fmac_f32_e32 v137, v145, v234
	v_fmac_f32_e32 v133, v145, v235
	s_waitcnt lgkmcnt(0)
	v_fmac_f32_e32 v128, v145, v236
	global_store_short v[0:1], v154, off offset:512
	v_mul_f32_e32 v154, v38, v144
	v_cvt_pk_bf16_f32 v155, v154, v5
	v_fmac_f32_e32 v136, v145, v237
	v_fmac_f32_e32 v131, v145, v238
	v_fmac_f32_e32 v126, v145, v239
	s_waitcnt lgkmcnt(0)
; #define LAS __attribute__((address_space(3)))
; __device__ __forceinline__ unsigned cvt_pk_bf16(float lo, float hi) { unsigned r; asm volatile("v_cvt_pk_bf16_f32 %0, %1, %2" : "=v"(r) : "v"(lo), "v"(hi)); return r; }
; __device__ __forceinline__ void p0_phase(const Args& a, LAS unsigned char* lds, int tid, int lane, int wave) {
;     ...
;                 for (int j = 0; j < 16; ++j) { const float xn = xa[u][j] * rstd * gm[j];
;                     XN[(size_t)row * D + lane + 64 * j] = (bf16_t)(cvt_pk_bf16(xn, 0.f) & 0xffffu);
;                     const LAS f32x4* wp = (const LAS f32x4*)(wfl + (lane + 64 * j) * 16);
; #pragma unroll
;                     for (int q = 0; q < 4; ++q) { const f32x4 w = wp[q]; f[4 * q + 0] += xn * w[0]; f[4 * q + 1] += xn * w[1]; f[4 * q + 2] += xn * w[2]; f[4 * q + 3] += xn * w[3]; } }
	v_fmac_f32_e32 v135, v154, v240
	v_fmac_f32_e32 v130, v154, v241
	v_mul_f32_e32 v143, v143, v139
	s_waitcnt lgkmcnt(0)
	v_fmac_f32_e32 v122, v154, v244
	v_fmac_f32_e32 v124, v154, v245
	v_fmac_f32_e32 v123, v154, v246
	v_fmac_f32_e32 v121, v154, v247
	ds_read_b128 v[144:147], v69 offset:48
	v_fmac_f32_e32 v129, v154, v242
	s_waitcnt lgkmcnt(1)
	v_fmac_f32_e32 v140, v154, v248
	v_fmac_f32_e32 v138, v154, v249
	v_fmac_f32_e32 v137, v154, v250
	v_fmac_f32_e32 v133, v154, v251
	s_waitcnt lgkmcnt(0)
	v_fmac_f32_e32 v128, v154, v144
	global_store_short v[0:1], v155, off offset:640
	v_mul_f32_e32 v143, v39, v143
	v_cvt_pk_bf16_f32 v152, v143, v5
	ds_read_b128 v[148:151], v70
	v_fmac_f32_e32 v136, v154, v145
	v_fmac_f32_e32 v131, v154, v146
	v_fmac_f32_e32 v126, v154, v147
	ds_read_b128 v[144:147], v70 offset:16
	v_fmac_f32_e32 v125, v154, v243
	s_waitcnt lgkmcnt(1)
	v_fmac_f32_e32 v135, v143, v148
	v_fmac_f32_e32 v130, v143, v149
	v_fmac_f32_e32 v129, v143, v150
	v_fmac_f32_e32 v125, v143, v151
	s_waitcnt lgkmcnt(0)
	v_fmac_f32_e32 v122, v143, v144
	ds_read_b128 v[148:151], v70 offset:32
	v_fmac_f32_e32 v124, v143, v145
	v_fmac_f32_e32 v123, v143, v146
	v_fmac_f32_e32 v121, v143, v147
	ds_read_b128 v[144:147], v70 offset:48
	v_mul_f32_e32 v142, v142, v139
	s_waitcnt lgkmcnt(1)
	v_fmac_f32_e32 v140, v143, v148
	v_fmac_f32_e32 v138, v143, v149
	v_fmac_f32_e32 v137, v143, v150
	v_fmac_f32_e32 v133, v143, v151
	s_waitcnt lgkmcnt(0)
	v_fmac_f32_e32 v128, v143, v144
	global_store_short v[0:1], v152, off offset:768
	v_mul_f32_e32 v152, v40, v142
	v_cvt_pk_bf16_f32 v153, v152, v5
	ds_read_b128 v[148:151], v71
	v_fmac_f32_e32 v136, v143, v145
	v_fmac_f32_e32 v131, v143, v146
	v_fmac_f32_e32 v126, v143, v147
	ds_read_b128 v[142:145], v71 offset:16
	s_waitcnt lgkmcnt(1)
	v_fmac_f32_e32 v135, v152, v148
	v_fmac_f32_e32 v130, v152, v149
	ds_read_b128 v[146:149], v71 offset:32
	v_mul_f32_e32 v141, v141, v139
	s_waitcnt lgkmcnt(1)
	v_fmac_f32_e32 v122, v152, v142
	v_fmac_f32_e32 v124, v152, v143
	v_fmac_f32_e32 v123, v152, v144
	v_fmac_f32_e32 v121, v152, v145
	ds_read_b128 v[142:145], v71 offset:48
	v_fmac_f32_e32 v129, v152, v150
	s_waitcnt lgkmcnt(1)
	v_fmac_f32_e32 v140, v152, v146
	v_fmac_f32_e32 v138, v152, v147
	v_fmac_f32_e32 v137, v152, v148
	v_fmac_f32_e32 v133, v152, v149
	s_waitcnt lgkmcnt(0)
	v_fmac_f32_e32 v128, v152, v142
	global_store_short v[0:1], v153, off offset:896
	v_mul_f32_e32 v141, v41, v141
	v_cvt_pk_bf16_f32 v150, v141, v5
	ds_read_b128 v[146:149], v72
	v_fmac_f32_e32 v136, v152, v143
	v_fmac_f32_e32 v131, v152, v144
	v_fmac_f32_e32 v126, v152, v145
	ds_read_b128 v[142:145], v72 offset:16
	v_fmac_f32_e32 v125, v152, v151
	s_waitcnt lgkmcnt(1)
	v_fmac_f32_e32 v135, v141, v146
	v_fmac_f32_e32 v130, v141, v147
	v_fmac_f32_e32 v129, v141, v148
	v_fmac_f32_e32 v125, v141, v149
	s_waitcnt lgkmcnt(0)
	v_fmac_f32_e32 v122, v141, v142
	ds_read_b128 v[146:149], v72 offset:32
	v_fmac_f32_e32 v124, v141, v143
	v_fmac_f32_e32 v123, v141, v144
	v_fmac_f32_e32 v121, v141, v145
	ds_read_b128 v[142:145], v72 offset:48
	v_mul_f32_e32 v127, v127, v139
	s_waitcnt lgkmcnt(1)
	v_fmac_f32_e32 v140, v141, v146
	v_fmac_f32_e32 v138, v141, v147
	v_fmac_f32_e32 v137, v141, v148
	v_fmac_f32_e32 v133, v141, v149
	s_waitcnt lgkmcnt(0)
	v_fmac_f32_e32 v128, v141, v142
	global_store_short v[0:1], v150, off offset:1024
	v_mul_f32_e32 v127, v42, v127
	v_cvt_pk_bf16_f32 v150, v127, v5
	ds_read_b128 v[146:149], v73
	v_fmac_f32_e32 v136, v141, v143
	v_fmac_f32_e32 v131, v141, v144
	v_fmac_f32_e32 v126, v141, v145
	ds_read_b128 v[142:145], v73 offset:16
	s_waitcnt lgkmcnt(1)
	v_fmac_f32_e32 v135, v127, v146
	v_fmac_f32_e32 v130, v127, v147
	v_fmac_f32_e32 v129, v127, v148
	v_fmac_f32_e32 v125, v127, v149
	s_waitcnt lgkmcnt(0)
	v_fmac_f32_e32 v122, v127, v142
	ds_read_b128 v[146:149], v73 offset:32
	v_fmac_f32_e32 v124, v127, v143
	v_fmac_f32_e32 v123, v127, v144
	v_fmac_f32_e32 v121, v127, v145
	ds_read_b128 v[142:145], v73 offset:48
	v_mul_f32_e32 v120, v120, v139
	s_waitcnt lgkmcnt(1)
	v_fmac_f32_e32 v140, v127, v146
	v_fmac_f32_e32 v138, v127, v147
	v_fmac_f32_e32 v137, v127, v148
	v_fmac_f32_e32 v133, v127, v149
	s_waitcnt lgkmcnt(0)
	v_fmac_f32_e32 v128, v127, v142
	global_store_short v[0:1], v150, off offset:1152
	v_mul_f32_e32 v120, v43, v120
	v_cvt_pk_bf16_f32 v141, v120, v5
	ds_read_b128 v[146:149], v74
	v_fmac_f32_e32 v136, v127, v143
	v_fmac_f32_e32 v131, v127, v144
	v_fmac_f32_e32 v126, v127, v145
	ds_read_b128 v[142:145], v74 offset:16
	s_waitcnt lgkmcnt(1)
	v_fmac_f32_e32 v135, v120, v146
	v_fmac_f32_e32 v130, v120, v147
	v_fmac_f32_e32 v129, v120, v148
	v_fmac_f32_e32 v125, v120, v149
	s_waitcnt lgkmcnt(0)
	v_fmac_f32_e32 v122, v120, v142
	ds_read_b128 v[146:149], v74 offset:32
	v_fmac_f32_e32 v124, v120, v143
	v_fmac_f32_e32 v123, v120, v144
	v_fmac_f32_e32 v121, v120, v145
	ds_read_b128 v[142:145], v74 offset:48
	v_mul_f32_e32 v119, v119, v139
	s_waitcnt lgkmcnt(1)
	v_fmac_f32_e32 v140, v120, v146
	v_fmac_f32_e32 v138, v120, v147
	v_fmac_f32_e32 v137, v120, v148
	v_fmac_f32_e32 v133, v120, v149
	s_waitcnt lgkmcnt(0)
	v_fmac_f32_e32 v128, v120, v142
	global_store_short v[0:1], v141, off offset:1280
	v_mul_f32_e32 v119, v44, v119
	v_cvt_pk_bf16_f32 v127, v119, v5
	ds_read_b128 v[146:149], v75
	v_fmac_f32_e32 v136, v120, v143
	v_fmac_f32_e32 v131, v120, v144
	v_fmac_f32_e32 v126, v120, v145
	ds_read_b128 v[142:145], v75 offset:16
	s_waitcnt lgkmcnt(1)
	v_fmac_f32_e32 v135, v119, v146
	v_fmac_f32_e32 v130, v119, v147
	v_fmac_f32_e32 v129, v119, v148
	v_fmac_f32_e32 v125, v119, v149
	s_waitcnt lgkmcnt(0)
; #define LAS __attribute__((address_space(3)))
; __device__ __forceinline__ unsigned cvt_pk_bf16(float lo, float hi) { unsigned r; asm volatile("v_cvt_pk_bf16_f32 %0, %1, %2" : "=v"(r) : "v"(lo), "v"(hi)); return r; }
; __device__ __forceinline__ void p0_phase(const Args& a, LAS unsigned char* lds, int tid, int lane, int wave) {
;     ...
;                 for (int j = 0; j < 16; ++j) { const float xn = xa[u][j] * rstd * gm[j];
;                     XN[(size_t)row * D + lane + 64 * j] = (bf16_t)(cvt_pk_bf16(xn, 0.f) & 0xffffu);
;                     const LAS f32x4* wp = (const LAS f32x4*)(wfl + (lane + 64 * j) * 16);
; #pragma unroll
;                     for (int q = 0; q < 4; ++q) { const f32x4 w = wp[q]; f[4 * q + 0] += xn * w[0]; f[4 * q + 1] += xn * w[1]; f[4 * q + 2] += xn * w[2]; f[4 * q + 3] += xn * w[3]; } }
;                 { const bool b5 = lane & 32;
; #pragma unroll
;                   for (int k = 0; k < 8; ++k) { const float send = b5 ? f[k] : f[k + 8], keep = b5 ? f[k + 8] : f[k]; f[k] = keep + __shfl_xor(send, 32); }
	v_fmac_f32_e32 v122, v119, v142
	ds_read_b128 v[146:149], v75 offset:32
	v_fmac_f32_e32 v124, v119, v143
	v_fmac_f32_e32 v123, v119, v144
	v_fmac_f32_e32 v121, v119, v145
	ds_read_b128 v[142:145], v75 offset:48
	v_mul_f32_e32 v118, v118, v139
	s_waitcnt lgkmcnt(1)
	v_fmac_f32_e32 v140, v119, v146
	v_fmac_f32_e32 v138, v119, v147
	v_fmac_f32_e32 v137, v119, v148
	v_fmac_f32_e32 v133, v119, v149
	s_waitcnt lgkmcnt(0)
	v_fmac_f32_e32 v128, v119, v142
	global_store_short v[0:1], v127, off offset:1408
	v_mul_f32_e32 v118, v45, v118
	v_cvt_pk_bf16_f32 v120, v118, v5
	ds_read_b128 v[146:149], v76
	v_fmac_f32_e32 v136, v119, v143
	v_fmac_f32_e32 v131, v119, v144
	v_fmac_f32_e32 v126, v119, v145
	ds_read_b128 v[142:145], v76 offset:16
	s_waitcnt lgkmcnt(1)
	v_fmac_f32_e32 v135, v118, v146
	v_fmac_f32_e32 v130, v118, v147
	v_fmac_f32_e32 v129, v118, v148
	v_fmac_f32_e32 v125, v118, v149
	s_waitcnt lgkmcnt(0)
	v_fmac_f32_e32 v122, v118, v142
	ds_read_b128 v[146:149], v76 offset:32
	v_fmac_f32_e32 v124, v118, v143
	v_fmac_f32_e32 v123, v118, v144
	v_fmac_f32_e32 v121, v118, v145
	ds_read_b128 v[142:145], v76 offset:48
	v_mul_f32_e32 v117, v117, v139
	s_waitcnt lgkmcnt(1)
	v_fmac_f32_e32 v140, v118, v146
	v_fmac_f32_e32 v138, v118, v147
	v_fmac_f32_e32 v137, v118, v148
	v_fmac_f32_e32 v133, v118, v149
	s_waitcnt lgkmcnt(0)
	v_fmac_f32_e32 v128, v118, v142
	global_store_short v[0:1], v120, off offset:1536
	v_mul_f32_e32 v120, v46, v117
	v_cvt_pk_bf16_f32 v117, v120, v5
	ds_read_b128 v[146:149], v77
	v_fmac_f32_e32 v136, v118, v143
	v_fmac_f32_e32 v131, v118, v144
	v_fmac_f32_e32 v126, v118, v145
	ds_read_b128 v[142:145], v77 offset:16
	s_waitcnt lgkmcnt(1)
	v_fmac_f32_e32 v135, v120, v146
	v_fmac_f32_e32 v130, v120, v147
	v_fmac_f32_e32 v129, v120, v148
	v_fmac_f32_e32 v125, v120, v149
	s_waitcnt lgkmcnt(0)
	v_fmac_f32_e32 v122, v120, v142
	ds_read_b128 v[146:149], v77 offset:32
	v_fmac_f32_e32 v124, v120, v143
	v_fmac_f32_e32 v123, v120, v144
	v_fmac_f32_e32 v121, v120, v145
	ds_read_b128 v[142:145], v77 offset:48
	v_mul_f32_e32 v116, v116, v139
	global_store_short v[0:1], v117, off offset:1664
	v_mul_f32_e32 v127, v47, v116
	v_cvt_pk_bf16_f32 v141, v127, v5
	ds_read_b128 v[116:119], v78
	s_waitcnt lgkmcnt(1)
	v_fmac_f32_e32 v128, v120, v142
	v_fmac_f32_e32 v136, v120, v143
	v_fmac_f32_e32 v131, v120, v144
	v_fmac_f32_e32 v126, v120, v145
	ds_read_b128 v[142:145], v78 offset:16
	s_waitcnt lgkmcnt(1)
	v_fmac_f32_e32 v135, v127, v116
	v_fmac_f32_e32 v130, v127, v117
	v_fmac_f32_e32 v129, v127, v118
	v_fmac_f32_e32 v125, v127, v119
	ds_read_b128 v[116:119], v78 offset:32
	s_waitcnt lgkmcnt(1)
	v_fmac_f32_e32 v122, v127, v142
	v_fmac_f32_e32 v124, v127, v143
	v_fmac_f32_e32 v123, v127, v144
	v_fmac_f32_e32 v121, v127, v145
	ds_read_b128 v[142:145], v78 offset:48
	v_fmac_f32_e32 v140, v120, v146
	v_fmac_f32_e32 v138, v120, v147
	v_fmac_f32_e32 v137, v120, v148
	v_fmac_f32_e32 v133, v120, v149
	v_mul_f32_e32 v33, v33, v139
	s_waitcnt lgkmcnt(1)
	v_fmac_f32_e32 v140, v127, v116
	v_fmac_f32_e32 v138, v127, v117
	v_fmac_f32_e32 v137, v127, v118
	v_fmac_f32_e32 v133, v127, v119
	global_store_short v[0:1], v141, off offset:1792
	v_mul_f32_e32 v33, v48, v33
	v_cvt_pk_bf16_f32 v120, v33, v5
	ds_read_b128 v[116:119], v79
	s_waitcnt lgkmcnt(1)
	v_fmac_f32_e32 v128, v127, v142
	v_fmac_f32_e32 v136, v127, v143
	v_fmac_f32_e32 v131, v127, v144
	v_fmac_f32_e32 v126, v127, v145
	ds_read_b128 v[142:145], v79 offset:16
	s_waitcnt lgkmcnt(1)
	v_fmac_f32_e32 v135, v33, v116
	v_fmac_f32_e32 v130, v33, v117
	v_fmac_f32_e32 v129, v33, v118
	v_fmac_f32_e32 v125, v33, v119
	ds_read_b128 v[116:119], v79 offset:32
	s_waitcnt lgkmcnt(1)
	v_fmac_f32_e32 v122, v33, v142
	v_fmac_f32_e32 v124, v33, v143
	v_fmac_f32_e32 v123, v33, v144
	v_fmac_f32_e32 v121, v33, v145
	ds_read_b128 v[142:145], v79 offset:48
	s_waitcnt lgkmcnt(1)
	v_fmac_f32_e32 v140, v33, v116
	v_fmac_f32_e32 v138, v33, v117
	v_fmac_f32_e32 v137, v33, v118
	v_fmac_f32_e32 v133, v33, v119
	s_waitcnt lgkmcnt(0)
	v_fmac_f32_e32 v128, v33, v142
	v_fmac_f32_e32 v136, v33, v143
	v_fmac_f32_e32 v131, v33, v144
	v_fmac_f32_e32 v126, v33, v145
	v_cndmask_b32_e64 v33, v135, v140, s[26:27]
	v_mov_b32_e32 v253, v33
	s_nop 1
	v_permlane32_swap_b32_e32 v33, v253
	v_cndmask_b32_e64 v33, v33, v253, s[26:27]
	v_cndmask_b32_e64 v117, v130, v138, s[26:27]
	v_mov_b32_e32 v253, v117
	s_nop 1
	v_permlane32_swap_b32_e32 v117, v253
	v_cndmask_b32_e64 v117, v117, v253, s[26:27]
	v_cndmask_b32_e64 v118, v129, v137, s[26:27]
	v_mov_b32_e32 v253, v118
	s_nop 1
	v_permlane32_swap_b32_e32 v118, v253
	v_cndmask_b32_e64 v118, v118, v253, s[26:27]
	v_cndmask_b32_e64 v116, v140, v135, s[26:27]
	s_waitcnt lgkmcnt(0)
	v_add_f32_e32 v33, v116, v33
	v_cndmask_b32_e64 v116, v138, v130, s[26:27]
	s_waitcnt lgkmcnt(0)
	v_add_f32_e32 v116, v116, v117
	v_cndmask_b32_e64 v117, v137, v129, s[26:27]
	s_waitcnt lgkmcnt(0)
	v_add_f32_e32 v117, v117, v118
	v_cndmask_b32_e64 v118, v125, v133, s[26:27]
	v_cndmask_b32_e64 v119, v133, v125, s[26:27]
	v_mov_b32_e32 v253, v118
	s_nop 1
	v_permlane32_swap_b32_e32 v118, v253
	v_cndmask_b32_e64 v118, v118, v253, s[26:27]
	v_cndmask_b32_e64 v125, v122, v128, s[26:27]
	v_mov_b32_e32 v253, v125
	s_nop 1
	v_permlane32_swap_b32_e32 v125, v253
	v_cndmask_b32_e64 v125, v125, v253, s[26:27]
	v_cndmask_b32_e64 v127, v124, v136, s[26:27]
	v_mov_b32_e32 v253, v127
	s_nop 1
	v_permlane32_swap_b32_e32 v127, v253
	v_cndmask_b32_e64 v127, v127, v253, s[26:27]
	s_waitcnt lgkmcnt(0)
	v_add_f32_e32 v118, v119, v118
	v_cndmask_b32_e64 v119, v128, v122, s[26:27]
	s_waitcnt lgkmcnt(0)
; __device__ __forceinline__ void p0_phase(const Args& a, LAS unsigned char* lds, int tid, int lane, int wave) {
;     ...
;                 { const bool b5 = lane & 32;
; #pragma unroll
;                   for (int k = 0; k < 8; ++k) { const float send = b5 ? f[k] : f[k + 8], keep = b5 ? f[k + 8] : f[k]; f[k] = keep + __shfl_xor(send, 32); }
;                   const bool b4 = lane & 16;
; #pragma unroll
;                   for (int k = 0; k < 4; ++k) { const float send = b4 ? f[k] : f[k + 4], keep = b4 ? f[k + 4] : f[k]; f[k] = keep + __shfl_xor(send, 16); }
;                   const bool b3 = lane & 8;
; #pragma unroll
;                   for (int k = 0; k < 2; ++k) { const float send = b3 ? f[k] : f[k + 2], keep = b3 ? f[k + 2] : f[k]; f[k] = keep + __shfl_xor(send, 8); }
;                   const bool b2 = lane & 4;
;                   { const float send = b2 ? f[0] : f[1], keep = b2 ? f[1] : f[0]; f[0] = keep + __shfl_xor(send, 4); }
;                   f[0] += __shfl_xor(f[0], 2); f[0] += __shfl_xor(f[0], 1); }
;                 if ((lane & 3) == 0) { const int hh = ((lane >> 5) & 1) * 8 + ((lane >> 4) & 1) * 4 + ((lane >> 3) & 1) * 2 + ((lane >> 2) & 1);
;                     const float z = f[0] + bfg[hh]; const float lg = fminf(z, 0.f) - log1pf(expf(-fabsf(z)));
;                     lf[rl * 16 + hh] = lg;
;                     if (row < MP) a.out[O_LFP + (size_t)row * NH + hh] = lg; else a.out[O_LFS + (size_t)(row - MP) * NH + hh] = lg; }
	v_add_f32_e32 v119, v119, v125
	v_cndmask_b32_e64 v122, v136, v124, s[26:27]
	v_cndmask_b32_e64 v124, v123, v131, s[26:27]
	v_cndmask_b32_e64 v125, v121, v126, s[26:27]
	v_mov_b32_e32 v253, v124
	s_nop 1
	v_permlane32_swap_b32_e32 v124, v253
	v_cndmask_b32_e64 v124, v124, v253, s[26:27]
	v_mov_b32_e32 v253, v125
	s_nop 1
	v_permlane32_swap_b32_e32 v125, v253
	v_cndmask_b32_e64 v125, v125, v253, s[26:27]
	v_cndmask_b32_e64 v123, v131, v123, s[26:27]
	v_cndmask_b32_e64 v121, v126, v121, s[26:27]
	s_waitcnt lgkmcnt(0)
	v_add_f32_e32 v122, v122, v127
	s_waitcnt lgkmcnt(0)
	v_add_f32_e32 v123, v123, v124
	s_waitcnt lgkmcnt(0)
	v_add_f32_e32 v121, v121, v125
	v_cndmask_b32_e64 v127, v33, v119, s[28:29]
	v_cndmask_b32_e64 v33, v119, v33, s[28:29]
	v_cndmask_b32_e64 v119, v116, v122, s[28:29]
	v_cndmask_b32_e64 v116, v122, v116, s[28:29]
	v_cndmask_b32_e64 v122, v117, v123, s[28:29]
	v_cndmask_b32_e64 v124, v118, v121, s[28:29]
	v_mov_b32_e32 v253, v127
	s_nop 1
	v_permlane16_swap_b32_e32 v127, v253
	v_cndmask_b32_e64 v127, v127, v253, s[28:29]
	v_mov_b32_e32 v253, v119
	s_nop 1
	v_permlane16_swap_b32_e32 v119, v253
	v_cndmask_b32_e64 v119, v119, v253, s[28:29]
	v_mov_b32_e32 v253, v122
	s_nop 1
	v_permlane16_swap_b32_e32 v122, v253
	v_cndmask_b32_e64 v122, v122, v253, s[28:29]
	v_mov_b32_e32 v253, v124
	s_nop 1
	v_permlane16_swap_b32_e32 v124, v253
	v_cndmask_b32_e64 v124, v124, v253, s[28:29]
	v_cndmask_b32_e64 v117, v123, v117, s[28:29]
	v_cndmask_b32_e64 v118, v121, v118, s[28:29]
	s_waitcnt lgkmcnt(0)
	v_add_f32_e32 v33, v33, v127
	s_waitcnt lgkmcnt(0)
	v_add_f32_e32 v116, v116, v119
	s_waitcnt lgkmcnt(0)
	v_add_f32_e32 v117, v117, v122
	s_waitcnt lgkmcnt(0)
	v_add_f32_e32 v118, v118, v124
	v_cndmask_b32_e64 v119, v33, v117, s[30:31]
	v_cndmask_b32_e64 v121, v116, v118, s[30:31]
	s_nop 1
	v_mov_b32_dpp v119, v119 row_ror:8 row_mask:0xf bank_mask:0xf
	s_nop 1
	v_mov_b32_dpp v121, v121 row_ror:8 row_mask:0xf bank_mask:0xf
	v_cndmask_b32_e64 v33, v117, v33, s[30:31]
	v_cndmask_b32_e64 v116, v118, v116, s[30:31]
	global_store_short v[0:1], v120, off offset:1920
	s_waitcnt lgkmcnt(0)
	v_add_f32_e32 v33, v33, v119
	s_waitcnt lgkmcnt(0)
	v_add_f32_e32 v116, v116, v121
	v_cndmask_b32_e64 v117, v33, v116, s[34:35]
	v_mov_b32_e32 v253, v117
	s_nop 1
	v_mov_b32_dpp v117, v253 row_shl:4 row_mask:0xf bank_mask:0x5
	s_nop 1
	v_mov_b32_dpp v117, v253 row_shr:4 row_mask:0xf bank_mask:0xa
	v_cndmask_b32_e64 v33, v116, v33, s[34:35]
	s_waitcnt lgkmcnt(0)
	v_add_f32_e32 v33, v33, v117
	s_nop 1
	v_mov_b32_dpp v116, v33 quad_perm:[2,3,0,1] row_mask:0xf bank_mask:0xf
	s_waitcnt lgkmcnt(0)
	v_add_f32_e32 v116, v33, v116
	s_nop 1
	v_mov_b32_dpp v117, v116 quad_perm:[1,0,3,2] row_mask:0xf bank_mask:0xf
	v_lshlrev_b32_e32 v33, 2, v8
	s_and_saveexec_b64 s[92:93], s[36:37]
	s_cbranch_execz .LBB0_35
	global_load_dword v0, v[10:11], off
	s_waitcnt lgkmcnt(0)
	v_add_f32_e32 v1, v116, v117
	s_add_i32 s11, s0, 0xffffc000
	s_cmpk_lt_i32 s0, 0x4000
	s_cselect_b32 s1, s1, 0
	s_cselect_b32 s0, s0, s11
	s_cselect_b32 s11, s7, 0xcd04000
	s_lshl_b64 s[0:1], s[0:1], 6
	s_add_u32 s0, s86, s0
	s_addc_u32 s1, s87, s1
	s_add_u32 s0, s0, s11
	v_lshl_add_u32 v116, s10, 6, v51
	s_addc_u32 s1, s1, 0
	s_waitcnt vmcnt(0)
	v_add_f32_e32 v0, v1, v0
	v_mul_f32_e64 v1, |v0|, s70
	v_fma_f32 v117, |v0|, s70, -v1
	v_rndne_f32_e32 v118, v1
	v_fma_f32 v117, |v0|, s71, v117
	v_sub_f32_e32 v1, v1, v118
	v_add_f32_e32 v1, v1, v117
	v_cvt_i32_f32_e32 v118, v118
	v_exp_f32_e32 v1, v1
	v_cmp_ngt_f32_e64 vcc, |v0|, s50
	v_min_f32_e32 v117, 0, v0
	v_ldexp_f32 v1, v1, v118
	v_cndmask_b32_e32 v1, 0, v1, vcc
	v_cmp_nlt_f32_e64 vcc, |v0|, s94
	s_nop 1
	v_cndmask_b32_e32 v118, v63, v1, vcc
	v_add_f32_e32 v119, 1.0, v118
	v_add_f32_e32 v120, -1.0, v119
	v_frexp_mant_f32_e32 v121, v119
	v_cvt_f64_f32_e32 v[0:1], v119
	v_sub_f32_e32 v122, v120, v119
	v_frexp_exp_i32_f64_e32 v0, v[0:1]
	v_cmp_gt_f32_e32 vcc, s4, v121
	v_sub_f32_e32 v120, v118, v120
	v_add_f32_e32 v1, 1.0, v122
	v_subbrev_co_u32_e32 v0, vcc, 0, v0, vcc
	v_add_f32_e32 v1, v120, v1
	v_sub_u32_e32 v120, 0, v0
	v_cvt_f32_i32_e32 v0, v0
	v_ldexp_f32 v119, v119, v120
	v_ldexp_f32 v1, v1, v120
	v_add_f32_e32 v120, -1.0, v119
	v_add_f32_e32 v121, 1.0, v119
	v_add_f32_e32 v122, 1.0, v120
	v_add_f32_e32 v123, -1.0, v121
	v_sub_f32_e32 v122, v119, v122
	v_sub_f32_e32 v119, v119, v123
	v_mul_f32_e32 v123, 0x3f317218, v0
	v_add_f32_e32 v122, v1, v122
	v_add_f32_e32 v1, v1, v119
	v_fma_f32 v119, v0, s5, -v123
	v_add_f32_e32 v124, v120, v122
	v_add_f32_e32 v125, v121, v1
	v_fmac_f32_e32 v119, 0xb102e308, v0
	v_sub_f32_e32 v0, v120, v124
	v_sub_f32_e32 v120, v121, v125
	v_rcp_f32_e32 v121, v125
	v_add_f32_e32 v126, v123, v119
	v_add_f32_e32 v1, v1, v120
	v_sub_f32_e32 v120, v126, v123
	v_sub_f32_e32 v119, v119, v120
	v_mul_f32_e32 v120, v124, v121
	v_add_f32_e32 v0, v122, v0
	v_mul_f32_e32 v122, v125, v120
	v_fma_f32 v123, v120, v125, -v122
	v_fmac_f32_e32 v123, v120, v1
	v_add_f32_e32 v127, v122, v123
	v_sub_f32_e32 v128, v124, v127
	v_sub_f32_e32 v122, v127, v122
	v_sub_f32_e32 v124, v124, v128
	v_sub_f32_e32 v122, v122, v123
	v_sub_f32_e32 v123, v124, v127
	v_add_f32_e32 v0, v0, v123
	v_add_f32_e32 v0, v122, v0
	v_add_f32_e32 v122, v128, v0
	v_mul_f32_e32 v123, v121, v122
	v_sub_f32_e32 v124, v128, v122
	v_mul_f32_e32 v127, v125, v123
	v_add_f32_e32 v0, v0, v124
	v_add_f32_e32 v124, v120, v123
	v_fma_f32 v125, v123, v125, -v127
	v_sub_f32_e32 v120, v124, v120
	v_fmac_f32_e32 v125, v123, v1
	v_sub_f32_e32 v1, v123, v120
	v_add_f32_e32 v120, v127, v125
	v_sub_f32_e32 v123, v120, v127
	v_sub_f32_e32 v127, v122, v120
	v_sub_f32_e32 v122, v122, v127
; #define LAS __attribute__((address_space(3)))
; __device__ __forceinline__ unsigned cvt_pk_bf16(float lo, float hi) { unsigned r; asm volatile("v_cvt_pk_bf16_f32 %0, %1, %2" : "=v"(r) : "v"(lo), "v"(hi)); return r; }
; __device__ __forceinline__ void p0_phase(const Args& a, LAS unsigned char* lds, int tid, int lane, int wave) {
;     ...
;                 float ss = 0.f;
; #pragma unroll
;                 for (int j = 0; j < 16; ++j) ss += xa[u][j] * xa[u][j];
;                 const float rstd = 1.0f / sqrtf(wave_sum(ss) * (1.f / D) + EPS);
;                 float f[16];
; #pragma unroll
;                 for (int h = 0; h < 16; ++h) f[h] = 0.f;
; #pragma unroll
;                 for (int j = 0; j < 16; ++j) { const float xn = xa[u][j] * rstd * gm[j];
;                     XN[(size_t)row * D + lane + 64 * j] = (bf16_t)(cvt_pk_bf16(xn, 0.f) & 0xffffu);
;                     const LAS f32x4* wp = (const LAS f32x4*)(wfl + (lane + 64 * j) * 16);
; #pragma unroll
;                     for (int q = 0; q < 4; ++q) { const f32x4 w = wp[q]; f[4 * q + 0] += xn * w[0]; f[4 * q + 1] += xn * w[1]; f[4 * q + 2] += xn * w[2]; f[4 * q + 3] += xn * w[3]; } }
;     ...
;                 if ((lane & 3) == 0) { const int hh = ((lane >> 5) & 1) * 8 + ((lane >> 4) & 1) * 4 + ((lane >> 3) & 1) * 2 + ((lane >> 2) & 1);
;                     const float z = f[0] + bfg[hh]; const float lg = fminf(z, 0.f) - log1pf(expf(-fabsf(z)));
;                     lf[rl * 16 + hh] = lg;
;                     if (row < MP) a.out[O_LFP + (size_t)row * NH + hh] = lg; else a.out[O_LFS + (size_t)(row - MP) * NH + hh] = lg; }
	v_sub_f32_e32 v120, v122, v120
	v_sub_f32_e32 v123, v123, v125
	v_add_f32_e32 v0, v0, v120
	v_add_f32_e32 v0, v123, v0
	v_add_f32_e32 v0, v127, v0
	v_mul_f32_e32 v0, v121, v0
	v_add_f32_e32 v0, v1, v0
	v_add_f32_e32 v1, v124, v0
	v_mul_f32_e32 v120, v1, v1
	v_fmamk_f32 v123, v120, 0x3e9b6dac, v62
	v_sub_f32_e32 v121, v1, v124
	v_ldexp_f32 v122, v1, 1
	v_mul_f32_e32 v1, v1, v120
	v_fmaak_f32 v120, v120, v123, 0x3f2aaada
	v_mul_f32_e32 v1, v1, v120
	v_add_f32_e32 v120, v122, v1
	v_sub_f32_e32 v0, v0, v121
	v_sub_f32_e32 v121, v120, v122
	v_ldexp_f32 v0, v0, 1
	v_sub_f32_e32 v1, v1, v121
	v_add_f32_e32 v0, v0, v1
	v_add_f32_e32 v1, v120, v0
	v_sub_f32_e32 v120, v1, v120
	v_add_f32_e32 v121, v126, v1
	v_sub_f32_e32 v0, v0, v120
	v_sub_f32_e32 v120, v121, v126
	v_sub_f32_e32 v122, v121, v120
	v_sub_f32_e32 v1, v1, v120
	v_add_f32_e32 v120, v119, v0
	v_sub_f32_e32 v122, v126, v122
	v_sub_f32_e32 v123, v120, v119
	v_add_f32_e32 v1, v1, v122
	v_sub_f32_e32 v122, v120, v123
	v_sub_f32_e32 v0, v0, v123
	v_sub_f32_e32 v119, v119, v122
	v_add_f32_e32 v1, v120, v1
	v_add_f32_e32 v0, v0, v119
	v_add_f32_e32 v119, v121, v1
	v_sub_f32_e32 v120, v119, v121
	v_sub_f32_e32 v1, v1, v120
	v_add_f32_e32 v0, v0, v1
	v_add_f32_e32 v0, v119, v0
	v_cmp_neq_f32_e32 vcc, s95, v118
	s_nop 1
	v_cndmask_b32_e32 v0, v63, v0, vcc
	v_cmp_lt_f32_e64 vcc, |v118|, s6
	s_nop 1
	v_cndmask_b32_e32 v0, v0, v118, vcc
	v_sub_f32_e32 v0, v117, v0
	ds_write_b32 v116, v0
	global_store_dword v33, v0, s[0:1]
.LBB0_35:
	s_or_b64 exec, exec, s[92:93]
	s_waitcnt vmcnt(59)
	v_mul_f32_e32 v0, v115, v115
	v_fmac_f32_e32 v0, v111, v111
	s_waitcnt vmcnt(58)
	v_fmac_f32_e32 v0, v114, v114
	s_waitcnt vmcnt(57)
	v_fmac_f32_e32 v0, v113, v113
	s_waitcnt vmcnt(56)
	v_fmac_f32_e32 v0, v112, v112
	s_waitcnt vmcnt(55)
	v_fmac_f32_e32 v0, v110, v110
	s_waitcnt vmcnt(54)
	v_fmac_f32_e32 v0, v109, v109
	s_waitcnt vmcnt(53)
	v_fmac_f32_e32 v0, v108, v108
	s_waitcnt vmcnt(52)
	v_fmac_f32_e32 v0, v107, v107
	s_waitcnt vmcnt(51)
	v_fmac_f32_e32 v0, v106, v106
	s_waitcnt vmcnt(50)
	v_fmac_f32_e32 v0, v105, v105
	s_waitcnt vmcnt(49)
	v_fmac_f32_e32 v0, v104, v104
	s_waitcnt vmcnt(48)
	v_fmac_f32_e32 v0, v103, v103
	s_waitcnt vmcnt(47)
	v_fmac_f32_e32 v0, v102, v102
	s_waitcnt vmcnt(46)
	v_fmac_f32_e32 v0, v101, v101
	v_fmac_f32_e32 v0, v100, v100
	s_nop 1
	v_mov_b32_dpp v1, v0 quad_perm:[1,0,3,2] row_mask:0xf bank_mask:0xf
	s_or_b32 s11, s10, 1
	s_add_i32 s92, s11, s45
	s_ashr_i32 s93, s92, 31
	s_lshl_b64 s[12:13], s[92:93], 11
	s_waitcnt lgkmcnt(0)
	v_add_f32_e32 v0, v0, v1
	s_nop 1
	v_mov_b32_dpp v1, v0 quad_perm:[2,3,0,1] row_mask:0xf bank_mask:0xf
	s_waitcnt lgkmcnt(0)
	v_add_f32_e32 v0, v0, v1
	s_nop 1
	v_mov_b32_dpp v1, v0 row_shl:4 row_mask:0xf bank_mask:0x5
	s_nop 1
	v_mov_b32_dpp v1, v0 row_shr:4 row_mask:0xf bank_mask:0xa
	s_waitcnt lgkmcnt(0)
	v_add_f32_e32 v0, v0, v1
	s_nop 1
	v_mov_b32_dpp v1, v0 row_ror:8 row_mask:0xf bank_mask:0xf
	s_waitcnt lgkmcnt(0)
	v_add_f32_e32 v0, v0, v1
	v_mov_b32_e32 v1, v0
	v_mov_b32_e32 v253, v0
	s_nop 1
	v_permlane16_swap_b32_e32 v1, v253
	v_cndmask_b32_e64 v1, v1, v253, s[28:29]
	s_waitcnt lgkmcnt(0)
	v_add_f32_e32 v0, v0, v1
	v_mov_b32_e32 v1, v0
	v_mov_b32_e32 v253, v0
	s_nop 1
	v_permlane32_swap_b32_e32 v1, v253
	v_cndmask_b32_e64 v1, v1, v253, s[26:27]
	s_waitcnt lgkmcnt(0)
	v_add_f32_e32 v0, v0, v1
	v_fmamk_f32 v0, v0, 0x3a800000, v60
	v_mul_f32_e32 v1, 0x4f800000, v0
	v_cmp_gt_f32_e32 vcc, s49, v0
	s_nop 1
	v_cndmask_b32_e32 v0, v0, v1, vcc
	v_sqrt_f32_e32 v1, v0
	s_nop 0
	v_add_u32_e32 v116, -1, v1
	v_add_u32_e32 v117, 1, v1
	v_fma_f32 v118, -v116, v1, v0
	v_fma_f32 v119, -v117, v1, v0
	v_cmp_ge_f32_e64 s[0:1], 0, v118
	s_nop 1
	v_cndmask_b32_e64 v1, v1, v116, s[0:1]
	v_cmp_lt_f32_e64 s[0:1], 0, v119
	s_nop 1
	v_cndmask_b32_e64 v1, v1, v117, s[0:1]
	v_mul_f32_e32 v116, 0x37800000, v1
	v_cndmask_b32_e32 v1, v1, v116, vcc
	v_cmp_class_f32_e32 vcc, v0, v61
	s_nop 1
	v_cndmask_b32_e32 v116, v1, v0, vcc
	v_div_scale_f32 v117, s[0:1], v116, v116, 1.0
	v_rcp_f32_e32 v118, v117
	v_div_scale_f32 v119, vcc, 1.0, v116, 1.0
	v_lshl_add_u64 v[0:1], v[6:7], 0, s[12:13]
	v_fma_f32 v120, -v117, v118, 1.0
	v_fmac_f32_e32 v118, v120, v118
	v_mul_f32_e32 v120, v119, v118
	v_fma_f32 v121, -v117, v120, v119
	v_fmac_f32_e32 v120, v121, v118
	v_fma_f32 v117, -v117, v120, v119
	v_div_fmas_f32 v117, v117, v118, v120
	v_div_fixup_f32 v131, v117, v116, 1.0
	v_mul_f32_e32 v111, v111, v131
	v_mul_f32_e32 v133, v9, v111
	v_cvt_pk_bf16_f32 v111, v133, v5
	v_mul_f32_e32 v115, v115, v131
	global_store_short v[0:1], v111, off
	s_waitcnt lgkmcnt(0)
	v_fma_f32 v129, v160, v133, 0
	v_fma_f32 v125, v161, v133, 0
	v_fma_f32 v124, v162, v133, 0
	v_fma_f32 v123, v163, v133, 0
	s_waitcnt lgkmcnt(0)
	v_fma_f32 v119, v164, v133, 0
	v_fma_f32 v118, v165, v133, 0
	v_fma_f32 v117, v166, v133, 0
	v_fma_f32 v111, v167, v133, 0
	s_waitcnt lgkmcnt(0)
	v_fma_f32 v130, v168, v133, 0
	v_fma_f32 v128, v169, v133, 0
	v_fma_f32 v127, v170, v133, 0
	v_fma_f32 v126, v171, v133, 0
	s_waitcnt lgkmcnt(0)
	v_fma_f32 v122, v133, v172, 0
	v_fma_f32 v121, v133, v173, 0
	v_fma_f32 v120, v133, v174, 0
	v_fma_f32 v116, v133, v175, 0
	v_mul_f32_e32 v115, v34, v115
	v_cvt_pk_bf16_f32 v133, v115, v5
	global_store_short v[0:1], v133, off offset:128
	v_mul_f32_e32 v114, v114, v131
	v_mul_f32_e32 v114, v35, v114
	s_waitcnt lgkmcnt(0)
	v_fmac_f32_e32 v119, v115, v180
	v_fmac_f32_e32 v129, v115, v176
	v_fmac_f32_e32 v125, v115, v177
	v_fmac_f32_e32 v124, v115, v178
	v_fmac_f32_e32 v123, v115, v179
	v_fmac_f32_e32 v118, v115, v181
	v_fmac_f32_e32 v117, v115, v182
	v_fmac_f32_e32 v111, v115, v183
	s_waitcnt lgkmcnt(0)
; #define LAS __attribute__((address_space(3)))
; __device__ __forceinline__ unsigned cvt_pk_bf16(float lo, float hi) { unsigned r; asm volatile("v_cvt_pk_bf16_f32 %0, %1, %2" : "=v"(r) : "v"(lo), "v"(hi)); return r; }
; __device__ __forceinline__ void p0_phase(const Args& a, LAS unsigned char* lds, int tid, int lane, int wave) {
;     ...
;                 for (int j = 0; j < 16; ++j) { const float xn = xa[u][j] * rstd * gm[j];
;                     XN[(size_t)row * D + lane + 64 * j] = (bf16_t)(cvt_pk_bf16(xn, 0.f) & 0xffffu);
;                     const LAS f32x4* wp = (const LAS f32x4*)(wfl + (lane + 64 * j) * 16);
; #pragma unroll
;                     for (int q = 0; q < 4; ++q) { const f32x4 w = wp[q]; f[4 * q + 0] += xn * w[0]; f[4 * q + 1] += xn * w[1]; f[4 * q + 2] += xn * w[2]; f[4 * q + 3] += xn * w[3]; } }
	v_fmac_f32_e32 v130, v115, v184
	v_fmac_f32_e32 v128, v115, v185
	v_fmac_f32_e32 v127, v115, v186
	v_fmac_f32_e32 v126, v115, v187
	s_waitcnt lgkmcnt(0)
	v_fmac_f32_e32 v122, v115, v188
	v_fmac_f32_e32 v121, v115, v189
	v_fmac_f32_e32 v120, v115, v190
	v_fmac_f32_e32 v116, v115, v191
	v_cvt_pk_bf16_f32 v115, v114, v5
	global_store_short v[0:1], v115, off offset:256
	v_mul_f32_e32 v113, v113, v131
	v_mul_f32_e32 v113, v36, v113
	s_waitcnt lgkmcnt(0)
	v_fmac_f32_e32 v119, v114, v196
	v_fmac_f32_e32 v129, v114, v192
	v_fmac_f32_e32 v125, v114, v193
	v_fmac_f32_e32 v124, v114, v194
	v_fmac_f32_e32 v123, v114, v195
	v_fmac_f32_e32 v118, v114, v197
	v_fmac_f32_e32 v117, v114, v198
	v_fmac_f32_e32 v111, v114, v199
	s_waitcnt lgkmcnt(0)
	v_fmac_f32_e32 v130, v114, v200
	v_fmac_f32_e32 v128, v114, v201
	v_fmac_f32_e32 v127, v114, v202
	v_fmac_f32_e32 v126, v114, v203
	s_waitcnt lgkmcnt(0)
	v_fmac_f32_e32 v122, v114, v204
	v_fmac_f32_e32 v121, v114, v205
	v_fmac_f32_e32 v120, v114, v206
	v_fmac_f32_e32 v116, v114, v207
	v_cvt_pk_bf16_f32 v114, v113, v5
	global_store_short v[0:1], v114, off offset:384
	v_mul_f32_e32 v112, v112, v131
	v_mul_f32_e32 v133, v37, v112
	v_cvt_pk_bf16_f32 v135, v133, v5
	global_store_short v[0:1], v135, off offset:512
	s_waitcnt lgkmcnt(0)
	v_fmac_f32_e32 v129, v113, v208
	v_fmac_f32_e32 v125, v113, v209
	v_fmac_f32_e32 v124, v113, v210
	v_fmac_f32_e32 v123, v113, v211
	s_waitcnt lgkmcnt(0)
	v_fmac_f32_e32 v119, v113, v212
	v_fmac_f32_e32 v118, v113, v213
	v_fmac_f32_e32 v117, v113, v214
	v_fmac_f32_e32 v111, v113, v215
	s_waitcnt lgkmcnt(0)
	v_fmac_f32_e32 v130, v113, v216
	v_fmac_f32_e32 v128, v113, v217
	v_fmac_f32_e32 v127, v113, v218
	v_fmac_f32_e32 v126, v113, v219
	s_waitcnt lgkmcnt(0)
	v_fmac_f32_e32 v122, v113, v220
	v_fmac_f32_e32 v121, v113, v221
	v_fmac_f32_e32 v120, v113, v222
	v_fmac_f32_e32 v116, v113, v223
	v_mul_f32_e32 v110, v110, v131
	v_mul_f32_e32 v110, v38, v110
	s_waitcnt lgkmcnt(0)
	v_fmac_f32_e32 v119, v133, v228
	v_fmac_f32_e32 v129, v133, v224
	v_fmac_f32_e32 v125, v133, v225
	v_fmac_f32_e32 v124, v133, v226
	v_fmac_f32_e32 v123, v133, v227
	v_fmac_f32_e32 v118, v133, v229
	v_fmac_f32_e32 v117, v133, v230
	v_fmac_f32_e32 v111, v133, v231
	s_waitcnt lgkmcnt(0)
	v_fmac_f32_e32 v130, v133, v232
	v_fmac_f32_e32 v128, v133, v233
	v_fmac_f32_e32 v127, v133, v234
	v_fmac_f32_e32 v126, v133, v235
	s_waitcnt lgkmcnt(0)
	v_fmac_f32_e32 v122, v133, v236
	v_fmac_f32_e32 v121, v133, v237
	v_fmac_f32_e32 v120, v133, v238
	v_fmac_f32_e32 v116, v133, v239
	v_cvt_pk_bf16_f32 v133, v110, v5
	global_store_short v[0:1], v133, off offset:640
	ds_read_b128 v[144:147], v69 offset:48
	v_mul_f32_e32 v109, v109, v131
	v_mul_f32_e32 v109, v39, v109
	s_waitcnt lgkmcnt(1)
	v_fmac_f32_e32 v119, v110, v244
	v_fmac_f32_e32 v129, v110, v240
	v_fmac_f32_e32 v125, v110, v241
	v_fmac_f32_e32 v124, v110, v242
	v_fmac_f32_e32 v123, v110, v243
	v_fmac_f32_e32 v118, v110, v245
	v_fmac_f32_e32 v117, v110, v246
	v_fmac_f32_e32 v111, v110, v247
	s_waitcnt lgkmcnt(1)
	v_fmac_f32_e32 v130, v110, v248
	v_fmac_f32_e32 v128, v110, v249
	v_fmac_f32_e32 v127, v110, v250
	v_fmac_f32_e32 v126, v110, v251
	s_waitcnt lgkmcnt(0)
	v_fmac_f32_e32 v122, v110, v144
	v_fmac_f32_e32 v121, v110, v145
	v_fmac_f32_e32 v120, v110, v146
	v_fmac_f32_e32 v116, v110, v147
	v_cvt_pk_bf16_f32 v110, v109, v5
	global_store_short v[0:1], v110, off offset:768
	ds_read_b128 v[112:115], v70
	ds_read_b128 v[136:139], v70 offset:16
	ds_read_b128 v[140:143], v70 offset:32
	ds_read_b128 v[144:147], v70 offset:48
	v_mul_f32_e32 v108, v108, v131
	v_mul_f32_e32 v108, v40, v108
	s_waitcnt lgkmcnt(2)
	v_fmac_f32_e32 v119, v109, v136
	v_fmac_f32_e32 v129, v109, v112
	v_fmac_f32_e32 v125, v109, v113
	v_fmac_f32_e32 v124, v109, v114
	v_fmac_f32_e32 v123, v109, v115
	v_fmac_f32_e32 v118, v109, v137
	v_fmac_f32_e32 v117, v109, v138
	v_fmac_f32_e32 v111, v109, v139
	s_waitcnt lgkmcnt(1)
	v_fmac_f32_e32 v130, v109, v140
	v_fmac_f32_e32 v128, v109, v141
	v_fmac_f32_e32 v127, v109, v142
	v_fmac_f32_e32 v126, v109, v143
	s_waitcnt lgkmcnt(0)
	v_fmac_f32_e32 v122, v109, v144
	v_fmac_f32_e32 v121, v109, v145
	v_fmac_f32_e32 v120, v109, v146
	v_fmac_f32_e32 v116, v109, v147
	v_cvt_pk_bf16_f32 v109, v108, v5
	global_store_short v[0:1], v109, off offset:896
	ds_read_b128 v[112:115], v71
	ds_read_b128 v[136:139], v71 offset:16
	ds_read_b128 v[140:143], v71 offset:32
	ds_read_b128 v[144:147], v71 offset:48
	v_mul_f32_e32 v107, v107, v131
	v_mul_f32_e32 v107, v41, v107
	s_waitcnt lgkmcnt(2)
	v_fmac_f32_e32 v119, v108, v136
	v_fmac_f32_e32 v129, v108, v112
	v_fmac_f32_e32 v125, v108, v113
	v_fmac_f32_e32 v124, v108, v114
	v_fmac_f32_e32 v123, v108, v115
	v_fmac_f32_e32 v118, v108, v137
	v_fmac_f32_e32 v117, v108, v138
	v_fmac_f32_e32 v111, v108, v139
	s_waitcnt lgkmcnt(1)
	v_fmac_f32_e32 v130, v108, v140
	v_fmac_f32_e32 v128, v108, v141
	v_fmac_f32_e32 v127, v108, v142
	v_fmac_f32_e32 v126, v108, v143
	s_waitcnt lgkmcnt(0)
	v_fmac_f32_e32 v122, v108, v144
	v_fmac_f32_e32 v121, v108, v145
	v_fmac_f32_e32 v120, v108, v146
	v_fmac_f32_e32 v116, v108, v147
	v_cvt_pk_bf16_f32 v108, v107, v5
	ds_read_b128 v[112:115], v72
	global_store_short v[0:1], v108, off offset:1024
	ds_read_b128 v[136:139], v72 offset:16
	ds_read_b128 v[140:143], v72 offset:32
	ds_read_b128 v[144:147], v72 offset:48
	v_mul_f32_e32 v106, v106, v131
	v_mul_f32_e32 v110, v42, v106
	s_waitcnt lgkmcnt(3)
	v_fmac_f32_e32 v129, v107, v112
	v_cvt_pk_bf16_f32 v112, v110, v5
	global_store_short v[0:1], v112, off offset:1152
	v_fmac_f32_e32 v125, v107, v113
	v_fmac_f32_e32 v124, v107, v114
	v_fmac_f32_e32 v123, v107, v115
	s_waitcnt lgkmcnt(2)
; #define LAS __attribute__((address_space(3)))
; __device__ __forceinline__ unsigned cvt_pk_bf16(float lo, float hi) { unsigned r; asm volatile("v_cvt_pk_bf16_f32 %0, %1, %2" : "=v"(r) : "v"(lo), "v"(hi)); return r; }
; __device__ __forceinline__ void p0_phase(const Args& a, LAS unsigned char* lds, int tid, int lane, int wave) {
;     ...
;                 for (int j = 0; j < 16; ++j) { const float xn = xa[u][j] * rstd * gm[j];
;                     XN[(size_t)row * D + lane + 64 * j] = (bf16_t)(cvt_pk_bf16(xn, 0.f) & 0xffffu);
;                     const LAS f32x4* wp = (const LAS f32x4*)(wfl + (lane + 64 * j) * 16);
; #pragma unroll
;                     for (int q = 0; q < 4; ++q) { const f32x4 w = wp[q]; f[4 * q + 0] += xn * w[0]; f[4 * q + 1] += xn * w[1]; f[4 * q + 2] += xn * w[2]; f[4 * q + 3] += xn * w[3]; } }
	v_fmac_f32_e32 v119, v107, v136
	v_fmac_f32_e32 v118, v107, v137
	v_fmac_f32_e32 v117, v107, v138
	v_fmac_f32_e32 v111, v107, v139
	s_waitcnt lgkmcnt(1)
	v_fmac_f32_e32 v130, v107, v140
	v_fmac_f32_e32 v128, v107, v141
	v_fmac_f32_e32 v127, v107, v142
	v_fmac_f32_e32 v126, v107, v143
	s_waitcnt lgkmcnt(0)
	v_fmac_f32_e32 v122, v107, v144
	v_fmac_f32_e32 v121, v107, v145
	v_fmac_f32_e32 v120, v107, v146
	v_fmac_f32_e32 v116, v107, v147
	ds_read_b128 v[106:109], v73
	ds_read_b128 v[112:115], v73 offset:16
	ds_read_b128 v[136:139], v73 offset:32
	ds_read_b128 v[140:143], v73 offset:48
	v_mul_f32_e32 v105, v105, v131
	v_mul_f32_e32 v105, v43, v105
	s_waitcnt lgkmcnt(2)
	v_fmac_f32_e32 v119, v110, v112
	v_fmac_f32_e32 v129, v110, v106
	v_fmac_f32_e32 v125, v110, v107
	v_fmac_f32_e32 v124, v110, v108
	v_fmac_f32_e32 v123, v110, v109
	v_fmac_f32_e32 v118, v110, v113
	v_fmac_f32_e32 v117, v110, v114
	v_fmac_f32_e32 v111, v110, v115
	s_waitcnt lgkmcnt(1)
	v_fmac_f32_e32 v130, v110, v136
	v_fmac_f32_e32 v128, v110, v137
	v_fmac_f32_e32 v127, v110, v138
	v_fmac_f32_e32 v126, v110, v139
	s_waitcnt lgkmcnt(0)
	v_fmac_f32_e32 v122, v110, v140
	v_fmac_f32_e32 v121, v110, v141
	v_fmac_f32_e32 v120, v110, v142
	v_fmac_f32_e32 v116, v110, v143
	v_cvt_pk_bf16_f32 v110, v105, v5
	ds_read_b128 v[106:109], v74
	global_store_short v[0:1], v110, off offset:1280
	ds_read_b128 v[112:115], v74 offset:16
	ds_read_b128 v[136:139], v74 offset:32
	ds_read_b128 v[140:143], v74 offset:48
	v_mul_f32_e32 v104, v104, v131
	v_mul_f32_e32 v103, v103, v131
	s_waitcnt lgkmcnt(3)
	v_fmac_f32_e32 v124, v105, v108
	v_fmac_f32_e32 v123, v105, v109
	v_mul_f32_e32 v108, v44, v104
	v_cvt_pk_bf16_f32 v109, v108, v5
	global_store_short v[0:1], v109, off offset:1408
	v_fmac_f32_e32 v129, v105, v106
	v_fmac_f32_e32 v125, v105, v107
	s_waitcnt lgkmcnt(2)
	v_fmac_f32_e32 v119, v105, v112
	v_fmac_f32_e32 v118, v105, v113
	v_fmac_f32_e32 v117, v105, v114
	v_fmac_f32_e32 v111, v105, v115
	s_waitcnt lgkmcnt(1)
	v_fmac_f32_e32 v130, v105, v136
	v_fmac_f32_e32 v128, v105, v137
	v_fmac_f32_e32 v127, v105, v138
	v_fmac_f32_e32 v126, v105, v139
	s_waitcnt lgkmcnt(0)
	v_fmac_f32_e32 v122, v105, v140
	v_fmac_f32_e32 v121, v105, v141
	v_fmac_f32_e32 v120, v105, v142
	v_fmac_f32_e32 v116, v105, v143
	ds_read_b128 v[104:107], v75
	ds_read_b128 v[112:115], v75 offset:16
	ds_read_b128 v[136:139], v75 offset:32
	ds_read_b128 v[140:143], v75 offset:48
	v_mul_f32_e32 v103, v45, v103
	v_mul_f32_e32 v102, v102, v131
	s_waitcnt lgkmcnt(2)
	v_fmac_f32_e32 v119, v108, v112
	v_fmac_f32_e32 v129, v108, v104
	v_fmac_f32_e32 v125, v108, v105
	v_fmac_f32_e32 v124, v108, v106
	v_fmac_f32_e32 v123, v108, v107
	v_fmac_f32_e32 v118, v108, v113
	v_fmac_f32_e32 v117, v108, v114
	v_fmac_f32_e32 v111, v108, v115
	s_waitcnt lgkmcnt(1)
	v_fmac_f32_e32 v130, v108, v136
	v_fmac_f32_e32 v128, v108, v137
	v_fmac_f32_e32 v127, v108, v138
	v_fmac_f32_e32 v126, v108, v139
	s_waitcnt lgkmcnt(0)
	v_fmac_f32_e32 v122, v108, v140
	v_fmac_f32_e32 v121, v108, v141
	v_fmac_f32_e32 v120, v108, v142
	v_fmac_f32_e32 v116, v108, v143
	v_cvt_pk_bf16_f32 v108, v103, v5
	ds_read_b128 v[104:107], v76
	global_store_short v[0:1], v108, off offset:1536
	ds_read_b128 v[112:115], v76 offset:16
	ds_read_b128 v[136:139], v76 offset:32
	ds_read_b128 v[140:143], v76 offset:48
	v_mul_f32_e32 v110, v46, v102
	v_mul_f32_e32 v101, v101, v131
	s_waitcnt lgkmcnt(3)
	v_fmac_f32_e32 v124, v103, v106
	v_cvt_pk_bf16_f32 v106, v110, v5
	global_store_short v[0:1], v106, off offset:1664
	v_fmac_f32_e32 v129, v103, v104
	v_fmac_f32_e32 v125, v103, v105
	v_fmac_f32_e32 v123, v103, v107
	s_waitcnt lgkmcnt(2)
	v_fmac_f32_e32 v119, v103, v112
	v_fmac_f32_e32 v118, v103, v113
	v_fmac_f32_e32 v117, v103, v114
	v_fmac_f32_e32 v111, v103, v115
	s_waitcnt lgkmcnt(1)
	v_fmac_f32_e32 v130, v103, v136
	v_fmac_f32_e32 v128, v103, v137
	v_fmac_f32_e32 v127, v103, v138
	v_fmac_f32_e32 v126, v103, v139
	s_waitcnt lgkmcnt(0)
	v_fmac_f32_e32 v122, v103, v140
	v_fmac_f32_e32 v121, v103, v141
	v_fmac_f32_e32 v120, v103, v142
	v_fmac_f32_e32 v116, v103, v143
	ds_read_b128 v[102:105], v77
	ds_read_b128 v[106:109], v77 offset:16
	ds_read_b128 v[112:115], v77 offset:32
	ds_read_b128 v[136:139], v77 offset:48
	v_mul_f32_e32 v100, v100, v131
	s_waitcnt lgkmcnt(2)
	v_fmac_f32_e32 v119, v110, v106
	v_fmac_f32_e32 v129, v110, v102
	v_fmac_f32_e32 v125, v110, v103
	v_fmac_f32_e32 v124, v110, v104
	v_fmac_f32_e32 v123, v110, v105
	v_fmac_f32_e32 v118, v110, v107
	v_fmac_f32_e32 v117, v110, v108
	v_fmac_f32_e32 v111, v110, v109
	s_waitcnt lgkmcnt(1)
	v_fmac_f32_e32 v130, v110, v112
	v_fmac_f32_e32 v128, v110, v113
	v_fmac_f32_e32 v127, v110, v114
	v_fmac_f32_e32 v126, v110, v115
	s_waitcnt lgkmcnt(0)
	v_fmac_f32_e32 v122, v110, v136
	v_fmac_f32_e32 v121, v110, v137
	v_fmac_f32_e32 v120, v110, v138
	v_fmac_f32_e32 v116, v110, v139
	v_mul_f32_e32 v110, v47, v101
	v_cvt_pk_bf16_f32 v101, v110, v5
	ds_read_b128 v[102:105], v78
	global_store_short v[0:1], v101, off offset:1792
	ds_read_b128 v[106:109], v78 offset:16
	ds_read_b128 v[112:115], v78 offset:32
	ds_read_b128 v[136:139], v78 offset:48
	s_waitcnt lgkmcnt(3)
	v_fmac_f32_e32 v129, v110, v102
	v_fmac_f32_e32 v125, v110, v103
	s_waitcnt lgkmcnt(2)
	v_fmac_f32_e32 v117, v110, v108
	v_fmac_f32_e32 v111, v110, v109
	v_mul_f32_e32 v108, v48, v100
	v_cvt_pk_bf16_f32 v109, v108, v5
	ds_read_b128 v[100:103], v79
	v_fmac_f32_e32 v124, v110, v104
	v_fmac_f32_e32 v123, v110, v105
	v_fmac_f32_e32 v119, v110, v106
	v_fmac_f32_e32 v118, v110, v107
	s_waitcnt lgkmcnt(2)
	v_fmac_f32_e32 v130, v110, v112
	v_fmac_f32_e32 v128, v110, v113
	v_fmac_f32_e32 v127, v110, v114
	v_fmac_f32_e32 v126, v110, v115
	s_waitcnt lgkmcnt(1)
; #define LAS __attribute__((address_space(3)))
; __device__ __forceinline__ unsigned cvt_pk_bf16(float lo, float hi) { unsigned r; asm volatile("v_cvt_pk_bf16_f32 %0, %1, %2" : "=v"(r) : "v"(lo), "v"(hi)); return r; }
; __device__ __forceinline__ void p0_phase(const Args& a, LAS unsigned char* lds, int tid, int lane, int wave) {
;     ...
;                 for (int j = 0; j < 16; ++j) { const float xn = xa[u][j] * rstd * gm[j];
;                     XN[(size_t)row * D + lane + 64 * j] = (bf16_t)(cvt_pk_bf16(xn, 0.f) & 0xffffu);
;                     const LAS f32x4* wp = (const LAS f32x4*)(wfl + (lane + 64 * j) * 16);
; #pragma unroll
;                     for (int q = 0; q < 4; ++q) { const f32x4 w = wp[q]; f[4 * q + 0] += xn * w[0]; f[4 * q + 1] += xn * w[1]; f[4 * q + 2] += xn * w[2]; f[4 * q + 3] += xn * w[3]; } }
;                 { const bool b5 = lane & 32;
; #pragma unroll
;                   for (int k = 0; k < 8; ++k) { const float send = b5 ? f[k] : f[k + 8], keep = b5 ? f[k + 8] : f[k]; f[k] = keep + __shfl_xor(send, 32); }
;                   const bool b4 = lane & 16;
; #pragma unroll
;                   for (int k = 0; k < 4; ++k) { const float send = b4 ? f[k] : f[k + 4], keep = b4 ? f[k + 4] : f[k]; f[k] = keep + __shfl_xor(send, 16); }
;                   const bool b3 = lane & 8;
; #pragma unroll
;                   for (int k = 0; k < 2; ++k) { const float send = b3 ? f[k] : f[k + 2], keep = b3 ? f[k + 2] : f[k]; f[k] = keep + __shfl_xor(send, 8); }
;                   const bool b2 = lane & 4;
;                   { const float send = b2 ? f[0] : f[1], keep = b2 ? f[1] : f[0]; f[0] = keep + __shfl_xor(send, 4); }
;                   f[0] += __shfl_xor(f[0], 2); f[0] += __shfl_xor(f[0], 1); }
;                 if ((lane & 3) == 0) { const int hh = ((lane >> 5) & 1) * 8 + ((lane >> 4) & 1) * 4 + ((lane >> 3) & 1) * 2 + ((lane >> 2) & 1);
	v_fmac_f32_e32 v122, v110, v136
	v_fmac_f32_e32 v121, v110, v137
	v_fmac_f32_e32 v120, v110, v138
	v_fmac_f32_e32 v116, v110, v139
	ds_read_b128 v[104:107], v79 offset:16
	ds_read_b128 v[112:115], v79 offset:32
	ds_read_b128 v[136:139], v79 offset:48
	s_waitcnt lgkmcnt(3)
	v_fmac_f32_e32 v129, v108, v100
	v_fmac_f32_e32 v125, v108, v101
	v_fmac_f32_e32 v124, v108, v102
	s_waitcnt lgkmcnt(1)
	v_fmac_f32_e32 v130, v108, v112
	v_fmac_f32_e32 v128, v108, v113
	v_cndmask_b32_e64 v100, v129, v130, s[26:27]
	v_fmac_f32_e32 v127, v108, v114
	v_mov_b32_e32 v253, v100
	s_nop 1
	v_permlane32_swap_b32_e32 v100, v253
	v_cndmask_b32_e64 v100, v100, v253, s[26:27]
	v_cndmask_b32_e64 v102, v125, v128, s[26:27]
	v_fmac_f32_e32 v123, v108, v103
	v_mov_b32_e32 v253, v102
	s_nop 1
	v_permlane32_swap_b32_e32 v102, v253
	v_cndmask_b32_e64 v102, v102, v253, s[26:27]
	v_cndmask_b32_e64 v103, v124, v127, s[26:27]
	v_mov_b32_e32 v253, v103
	s_nop 1
	v_permlane32_swap_b32_e32 v103, v253
	v_cndmask_b32_e64 v103, v103, v253, s[26:27]
	v_cndmask_b32_e64 v101, v130, v129, s[26:27]
	s_waitcnt lgkmcnt(0)
	v_add_f32_e32 v100, v101, v100
	v_cndmask_b32_e64 v101, v128, v125, s[26:27]
	v_fmac_f32_e32 v126, v108, v115
	s_waitcnt lgkmcnt(0)
	v_add_f32_e32 v101, v101, v102
	v_cndmask_b32_e64 v102, v127, v124, s[26:27]
	v_fmac_f32_e32 v119, v108, v104
	v_fmac_f32_e32 v122, v108, v136
	s_waitcnt lgkmcnt(0)
	v_add_f32_e32 v102, v102, v103
	v_cndmask_b32_e64 v103, v123, v126, s[26:27]
	v_fmac_f32_e32 v118, v108, v105
	v_fmac_f32_e32 v121, v108, v137
	v_mov_b32_e32 v253, v103
	s_nop 1
	v_permlane32_swap_b32_e32 v103, v253
	v_cndmask_b32_e64 v103, v103, v253, s[26:27]
	v_cndmask_b32_e64 v105, v119, v122, s[26:27]
	v_fmac_f32_e32 v117, v108, v106
	v_mov_b32_e32 v253, v105
	s_nop 1
	v_permlane32_swap_b32_e32 v105, v253
	v_cndmask_b32_e64 v105, v105, v253, s[26:27]
	v_cndmask_b32_e64 v106, v118, v121, s[26:27]
	v_mov_b32_e32 v253, v106
	s_nop 1
	v_permlane32_swap_b32_e32 v106, v253
	v_cndmask_b32_e64 v106, v106, v253, s[26:27]
	v_cndmask_b32_e64 v104, v126, v123, s[26:27]
	s_waitcnt lgkmcnt(0)
	v_add_f32_e32 v103, v104, v103
	v_cndmask_b32_e64 v104, v122, v119, s[26:27]
	v_fmac_f32_e32 v120, v108, v138
	s_waitcnt lgkmcnt(0)
	v_add_f32_e32 v104, v104, v105
	v_cndmask_b32_e64 v105, v121, v118, s[26:27]
	v_fmac_f32_e32 v111, v108, v107
	v_fmac_f32_e32 v116, v108, v139
	s_waitcnt lgkmcnt(0)
	v_add_f32_e32 v105, v105, v106
	v_cndmask_b32_e64 v106, v117, v120, s[26:27]
	v_mov_b32_e32 v253, v106
	s_nop 1
	v_permlane32_swap_b32_e32 v106, v253
	v_cndmask_b32_e64 v106, v106, v253, s[26:27]
	v_cndmask_b32_e64 v108, v111, v116, s[26:27]
	v_mov_b32_e32 v253, v108
	s_nop 1
	v_permlane32_swap_b32_e32 v108, v253
	v_cndmask_b32_e64 v108, v108, v253, s[26:27]
	v_cndmask_b32_e64 v107, v120, v117, s[26:27]
	v_cndmask_b32_e64 v110, v100, v104, s[28:29]
	s_waitcnt lgkmcnt(0)
	v_add_f32_e32 v106, v107, v106
	v_cndmask_b32_e64 v107, v116, v111, s[26:27]
	s_waitcnt lgkmcnt(0)
	v_add_f32_e32 v107, v107, v108
	v_cndmask_b32_e64 v100, v104, v100, s[28:29]
	v_cndmask_b32_e64 v104, v101, v105, s[28:29]
	v_cndmask_b32_e64 v101, v105, v101, s[28:29]
	v_cndmask_b32_e64 v105, v102, v106, s[28:29]
	v_cndmask_b32_e64 v108, v103, v107, s[28:29]
	v_mov_b32_e32 v253, v110
	s_nop 1
	v_permlane16_swap_b32_e32 v110, v253
	v_cndmask_b32_e64 v110, v110, v253, s[28:29]
	v_mov_b32_e32 v253, v104
	s_nop 1
	v_permlane16_swap_b32_e32 v104, v253
	v_cndmask_b32_e64 v104, v104, v253, s[28:29]
	v_mov_b32_e32 v253, v105
	s_nop 1
	v_permlane16_swap_b32_e32 v105, v253
	v_cndmask_b32_e64 v105, v105, v253, s[28:29]
	v_mov_b32_e32 v253, v108
	s_nop 1
	v_permlane16_swap_b32_e32 v108, v253
	v_cndmask_b32_e64 v108, v108, v253, s[28:29]
	v_cndmask_b32_e64 v102, v106, v102, s[28:29]
	v_cndmask_b32_e64 v103, v107, v103, s[28:29]
	s_waitcnt lgkmcnt(0)
	v_add_f32_e32 v100, v100, v110
	s_waitcnt lgkmcnt(0)
	v_add_f32_e32 v101, v101, v104
	s_waitcnt lgkmcnt(0)
	v_add_f32_e32 v102, v102, v105
	s_waitcnt lgkmcnt(0)
	v_add_f32_e32 v103, v103, v108
	v_cndmask_b32_e64 v104, v100, v102, s[30:31]
	v_cndmask_b32_e64 v105, v101, v103, s[30:31]
	s_nop 1
	v_mov_b32_dpp v104, v104 row_ror:8 row_mask:0xf bank_mask:0xf
	s_nop 1
	v_mov_b32_dpp v105, v105 row_ror:8 row_mask:0xf bank_mask:0xf
	v_cndmask_b32_e64 v100, v102, v100, s[30:31]
	v_cndmask_b32_e64 v101, v103, v101, s[30:31]
	global_store_short v[0:1], v109, off offset:1920
	s_waitcnt lgkmcnt(0)
	v_add_f32_e32 v100, v100, v104
	s_waitcnt lgkmcnt(0)
	v_add_f32_e32 v101, v101, v105
	v_cndmask_b32_e64 v102, v100, v101, s[34:35]
	v_mov_b32_e32 v253, v102
	s_nop 1
	v_mov_b32_dpp v102, v253 row_shl:4 row_mask:0xf bank_mask:0x5
	s_nop 1
	v_mov_b32_dpp v102, v253 row_shr:4 row_mask:0xf bank_mask:0xa
	v_cndmask_b32_e64 v100, v101, v100, s[34:35]
	s_waitcnt lgkmcnt(0)
	v_add_f32_e32 v100, v100, v102
	s_nop 1
	v_mov_b32_dpp v101, v100 quad_perm:[2,3,0,1] row_mask:0xf bank_mask:0xf
	s_waitcnt lgkmcnt(0)
	v_add_f32_e32 v100, v100, v101
	s_nop 1
	v_mov_b32_dpp v101, v100 quad_perm:[1,0,3,2] row_mask:0xf bank_mask:0xf
	s_and_saveexec_b64 s[0:1], s[36:37]
	s_cbranch_execz .LBB0_37
; __device__ __forceinline__ void p0_phase(const Args& a, LAS unsigned char* lds, int tid, int lane, int wave) {
;     ...
;                 if ((lane & 3) == 0) { const int hh = ((lane >> 5) & 1) * 8 + ((lane >> 4) & 1) * 4 + ((lane >> 3) & 1) * 2 + ((lane >> 2) & 1);
;                     const float z = f[0] + bfg[hh]; const float lg = fminf(z, 0.f) - log1pf(expf(-fabsf(z)));
;                     lf[rl * 16 + hh] = lg;
;                     if (row < MP) a.out[O_LFP + (size_t)row * NH + hh] = lg; else a.out[O_LFS + (size_t)(row - MP) * NH + hh] = lg; }
	global_load_dword v0, v[10:11], off
	s_waitcnt lgkmcnt(0)
	v_add_f32_e32 v1, v100, v101
	v_lshl_add_u32 v100, s11, 6, v51
	s_add_i32 s11, s92, 0xffffc000
	s_cmpk_lt_i32 s92, 0x4000
	s_cselect_b32 s13, s93, 0
	s_cselect_b32 s12, s92, s11
	s_cselect_b32 s11, s7, 0xcd04000
	s_lshl_b64 s[12:13], s[12:13], 6
	s_add_u32 s12, s86, s12
	s_addc_u32 s13, s87, s13
	s_add_u32 s92, s12, s11
	s_addc_u32 s93, s13, 0
	s_waitcnt vmcnt(0)
	v_add_f32_e32 v0, v1, v0
	v_mul_f32_e64 v1, |v0|, s70
	v_fma_f32 v101, |v0|, s70, -v1
	v_rndne_f32_e32 v102, v1
	v_fma_f32 v101, |v0|, s71, v101
	v_sub_f32_e32 v1, v1, v102
	v_add_f32_e32 v1, v1, v101
	v_cvt_i32_f32_e32 v102, v102
	v_exp_f32_e32 v1, v1
	v_cmp_ngt_f32_e64 vcc, |v0|, s50
	v_min_f32_e32 v101, 0, v0
	v_ldexp_f32 v1, v1, v102
	v_cndmask_b32_e32 v1, 0, v1, vcc
	v_cmp_nlt_f32_e64 vcc, |v0|, s94
	s_nop 1
	v_cndmask_b32_e32 v102, v63, v1, vcc
	v_add_f32_e32 v103, 1.0, v102
	v_add_f32_e32 v104, -1.0, v103
	v_frexp_mant_f32_e32 v105, v103
	v_cvt_f64_f32_e32 v[0:1], v103
	v_sub_f32_e32 v106, v104, v103
	v_frexp_exp_i32_f64_e32 v0, v[0:1]
	v_cmp_gt_f32_e32 vcc, s4, v105
	v_sub_f32_e32 v104, v102, v104
	v_add_f32_e32 v1, 1.0, v106
	v_subbrev_co_u32_e32 v0, vcc, 0, v0, vcc
	v_add_f32_e32 v1, v104, v1
	v_sub_u32_e32 v104, 0, v0
	v_cvt_f32_i32_e32 v0, v0
	v_ldexp_f32 v103, v103, v104
	v_ldexp_f32 v1, v1, v104
	v_add_f32_e32 v104, -1.0, v103
	v_add_f32_e32 v105, 1.0, v103
	v_add_f32_e32 v106, 1.0, v104
	v_add_f32_e32 v107, -1.0, v105
	v_sub_f32_e32 v106, v103, v106
	v_sub_f32_e32 v103, v103, v107
	v_mul_f32_e32 v107, 0x3f317218, v0
	v_add_f32_e32 v106, v1, v106
	v_add_f32_e32 v1, v1, v103
	v_fma_f32 v103, v0, s5, -v107
	v_add_f32_e32 v108, v104, v106
	v_add_f32_e32 v109, v105, v1
	v_fmac_f32_e32 v103, 0xb102e308, v0
	v_sub_f32_e32 v0, v104, v108
	v_sub_f32_e32 v104, v105, v109
	v_rcp_f32_e32 v105, v109
	v_add_f32_e32 v110, v107, v103
	v_add_f32_e32 v1, v1, v104
	v_sub_f32_e32 v104, v110, v107
	v_sub_f32_e32 v103, v103, v104
	v_mul_f32_e32 v104, v108, v105
	v_add_f32_e32 v0, v106, v0
	v_mul_f32_e32 v106, v109, v104
	v_fma_f32 v107, v104, v109, -v106
	v_fmac_f32_e32 v107, v104, v1
	v_add_f32_e32 v111, v106, v107
	v_sub_f32_e32 v112, v108, v111
	v_sub_f32_e32 v106, v111, v106
	v_sub_f32_e32 v108, v108, v112
	v_sub_f32_e32 v106, v106, v107
	v_sub_f32_e32 v107, v108, v111
	v_add_f32_e32 v0, v0, v107
	v_add_f32_e32 v0, v106, v0
	v_add_f32_e32 v106, v112, v0
	v_mul_f32_e32 v107, v105, v106
	v_sub_f32_e32 v108, v112, v106
	v_mul_f32_e32 v111, v109, v107
	v_add_f32_e32 v0, v0, v108
	v_add_f32_e32 v108, v104, v107
	v_fma_f32 v109, v107, v109, -v111
	v_sub_f32_e32 v104, v108, v104
	v_fmac_f32_e32 v109, v107, v1
	v_sub_f32_e32 v1, v107, v104
	v_add_f32_e32 v104, v111, v109
	v_sub_f32_e32 v107, v104, v111
	v_sub_f32_e32 v111, v106, v104
	v_sub_f32_e32 v106, v106, v111
	v_sub_f32_e32 v104, v106, v104
	v_sub_f32_e32 v107, v107, v109
	v_add_f32_e32 v0, v0, v104
	v_add_f32_e32 v0, v107, v0
	v_add_f32_e32 v0, v111, v0
	v_mul_f32_e32 v0, v105, v0
	v_add_f32_e32 v0, v1, v0
	v_add_f32_e32 v1, v108, v0
	v_mul_f32_e32 v104, v1, v1
	v_fmamk_f32 v107, v104, 0x3e9b6dac, v62
	v_sub_f32_e32 v105, v1, v108
	v_ldexp_f32 v106, v1, 1
	v_mul_f32_e32 v1, v1, v104
	v_fmaak_f32 v104, v104, v107, 0x3f2aaada
	v_mul_f32_e32 v1, v1, v104
	v_add_f32_e32 v104, v106, v1
	v_sub_f32_e32 v0, v0, v105
	v_sub_f32_e32 v105, v104, v106
	v_ldexp_f32 v0, v0, 1
	v_sub_f32_e32 v1, v1, v105
	v_add_f32_e32 v0, v0, v1
	v_add_f32_e32 v1, v104, v0
	v_sub_f32_e32 v104, v1, v104
	v_add_f32_e32 v105, v110, v1
	v_sub_f32_e32 v0, v0, v104
	v_sub_f32_e32 v104, v105, v110
	v_sub_f32_e32 v106, v105, v104
	v_sub_f32_e32 v1, v1, v104
	v_add_f32_e32 v104, v103, v0
	v_sub_f32_e32 v106, v110, v106
	v_sub_f32_e32 v107, v104, v103
	v_add_f32_e32 v1, v1, v106
	v_sub_f32_e32 v106, v104, v107
	v_sub_f32_e32 v0, v0, v107
	v_sub_f32_e32 v103, v103, v106
	v_add_f32_e32 v1, v104, v1
	v_add_f32_e32 v0, v0, v103
	v_add_f32_e32 v103, v105, v1
	v_sub_f32_e32 v104, v103, v105
	v_sub_f32_e32 v1, v1, v104
	v_add_f32_e32 v0, v0, v1
	v_add_f32_e32 v0, v103, v0
	v_cmp_neq_f32_e32 vcc, s95, v102
	s_nop 1
	v_cndmask_b32_e32 v0, v63, v0, vcc
	v_cmp_lt_f32_e64 vcc, |v102|, s6
	s_nop 1
	v_cndmask_b32_e32 v0, v0, v102, vcc
	v_sub_f32_e32 v0, v101, v0
	ds_write_b32 v100, v0
	global_store_dword v33, v0, s[92:93]
; #define LAS __attribute__((address_space(3)))
; __device__ __forceinline__ unsigned cvt_pk_bf16(float lo, float hi) { unsigned r; asm volatile("v_cvt_pk_bf16_f32 %0, %1, %2" : "=v"(r) : "v"(lo), "v"(hi)); return r; }
; __device__ __forceinline__ void p0_phase(const Args& a, LAS unsigned char* lds, int tid, int lane, int wave) {
;     ...
;                 for (int u = 0; u < 4; ++u) {
;                 const int rl = wave * 8 + i4 * 4 + u, row = c * 64 + rl;
;                 float ss = 0.f;
; #pragma unroll
;                 for (int j = 0; j < 16; ++j) ss += xa[u][j] * xa[u][j];
;                 const float rstd = 1.0f / sqrtf(wave_sum(ss) * (1.f / D) + EPS);
;                 float f[16];
; #pragma unroll
;                 for (int h = 0; h < 16; ++h) f[h] = 0.f;
; #pragma unroll
;                 for (int j = 0; j < 16; ++j) { const float xn = xa[u][j] * rstd * gm[j];
;                     XN[(size_t)row * D + lane + 64 * j] = (bf16_t)(cvt_pk_bf16(xn, 0.f) & 0xffffu);
;                     const LAS f32x4* wp = (const LAS f32x4*)(wfl + (lane + 64 * j) * 16);
; #pragma unroll
;                     for (int q = 0; q < 4; ++q) { const f32x4 w = wp[q]; f[4 * q + 0] += xn * w[0]; f[4 * q + 1] += xn * w[1]; f[4 * q + 2] += xn * w[2]; f[4 * q + 3] += xn * w[3]; } }
.LBB0_37:
	s_or_b64 exec, exec, s[0:1]
	s_waitcnt vmcnt(60)
	v_mul_f32_e32 v0, v98, v98
	v_fmac_f32_e32 v0, v99, v99
	s_waitcnt vmcnt(59)
	v_fmac_f32_e32 v0, v97, v97
	s_waitcnt vmcnt(58)
	v_fmac_f32_e32 v0, v96, v96
	s_waitcnt vmcnt(57)
	v_fmac_f32_e32 v0, v95, v95
	s_waitcnt vmcnt(56)
	v_fmac_f32_e32 v0, v94, v94
	s_waitcnt vmcnt(55)
	v_fmac_f32_e32 v0, v93, v93
	s_waitcnt vmcnt(54)
	v_fmac_f32_e32 v0, v92, v92
	s_waitcnt vmcnt(53)
	v_fmac_f32_e32 v0, v91, v91
	s_waitcnt vmcnt(52)
	v_fmac_f32_e32 v0, v90, v90
	s_waitcnt vmcnt(51)
	v_fmac_f32_e32 v0, v89, v89
	s_waitcnt vmcnt(50)
	v_fmac_f32_e32 v0, v88, v88
	s_waitcnt vmcnt(49)
	v_fmac_f32_e32 v0, v87, v87
	s_waitcnt vmcnt(48)
	v_fmac_f32_e32 v0, v86, v86
	s_waitcnt vmcnt(47)
	v_fmac_f32_e32 v0, v85, v85
	v_fmac_f32_e32 v0, v84, v84
	s_nop 1
	v_mov_b32_dpp v1, v0 quad_perm:[1,0,3,2] row_mask:0xf bank_mask:0xf
	s_or_b32 s11, s10, 2
	s_add_i32 s92, s11, s45
	s_ashr_i32 s93, s92, 31
	s_lshl_b64 s[12:13], s[92:93], 11
	s_waitcnt lgkmcnt(0)
	v_add_f32_e32 v0, v0, v1
	s_nop 1
	v_mov_b32_dpp v1, v0 quad_perm:[2,3,0,1] row_mask:0xf bank_mask:0xf
	s_waitcnt lgkmcnt(0)
	v_add_f32_e32 v0, v0, v1
	s_nop 1
	v_mov_b32_dpp v1, v0 row_shl:4 row_mask:0xf bank_mask:0x5
	s_nop 1
	v_mov_b32_dpp v1, v0 row_shr:4 row_mask:0xf bank_mask:0xa
	s_waitcnt lgkmcnt(0)
	v_add_f32_e32 v0, v0, v1
	s_nop 1
	v_mov_b32_dpp v1, v0 row_ror:8 row_mask:0xf bank_mask:0xf
	s_waitcnt lgkmcnt(0)
	v_add_f32_e32 v0, v0, v1
	v_mov_b32_e32 v1, v0
	v_mov_b32_e32 v253, v0
	s_nop 1
	v_permlane16_swap_b32_e32 v1, v253
	v_cndmask_b32_e64 v1, v1, v253, s[28:29]
	s_waitcnt lgkmcnt(0)
	v_add_f32_e32 v0, v0, v1
	v_mov_b32_e32 v1, v0
	v_mov_b32_e32 v253, v0
	s_nop 1
	v_permlane32_swap_b32_e32 v1, v253
	v_cndmask_b32_e64 v1, v1, v253, s[26:27]
	s_waitcnt lgkmcnt(0)
	v_add_f32_e32 v0, v0, v1
	v_fmamk_f32 v0, v0, 0x3a800000, v60
	v_mul_f32_e32 v1, 0x4f800000, v0
	v_cmp_gt_f32_e32 vcc, s49, v0
	s_nop 1
	v_cndmask_b32_e32 v0, v0, v1, vcc
	v_sqrt_f32_e32 v1, v0
	s_nop 0
	v_add_u32_e32 v100, -1, v1
	v_add_u32_e32 v101, 1, v1
	v_fma_f32 v102, -v100, v1, v0
	v_fma_f32 v103, -v101, v1, v0
	v_cmp_ge_f32_e64 s[0:1], 0, v102
	s_nop 1
	v_cndmask_b32_e64 v1, v1, v100, s[0:1]
	v_cmp_lt_f32_e64 s[0:1], 0, v103
	s_nop 1
	v_cndmask_b32_e64 v1, v1, v101, s[0:1]
	v_mul_f32_e32 v100, 0x37800000, v1
	v_cndmask_b32_e32 v1, v1, v100, vcc
	v_cmp_class_f32_e32 vcc, v0, v61
	s_nop 1
	v_cndmask_b32_e32 v100, v1, v0, vcc
	v_div_scale_f32 v101, s[0:1], v100, v100, 1.0
	v_rcp_f32_e32 v102, v101
	v_div_scale_f32 v103, vcc, 1.0, v100, 1.0
	v_lshl_add_u64 v[0:1], v[6:7], 0, s[12:13]
	v_fma_f32 v104, -v101, v102, 1.0
	v_fmac_f32_e32 v102, v104, v102
	v_mul_f32_e32 v104, v103, v102
	v_fma_f32 v105, -v101, v104, v103
	v_fmac_f32_e32 v104, v105, v102
	v_fma_f32 v101, -v101, v104, v103
	v_div_fmas_f32 v101, v101, v102, v104
	v_div_fixup_f32 v115, v101, v100, 1.0
	v_mul_f32_e32 v99, v99, v115
	v_mul_f32_e32 v128, v9, v99
	v_cvt_pk_bf16_f32 v99, v128, v5
	v_mul_f32_e32 v98, v98, v115
	global_store_short v[0:1], v99, off
	v_mul_f32_e32 v98, v34, v98
	s_waitcnt lgkmcnt(0)
	v_fma_f32 v114, v168, v128, 0
	v_cvt_pk_bf16_f32 v120, v98, v5
	global_store_short v[0:1], v120, off offset:128
	v_fma_f32 v113, v160, v128, 0
	v_fma_f32 v109, v161, v128, 0
	v_fma_f32 v108, v162, v128, 0
	v_fma_f32 v107, v163, v128, 0
	v_fma_f32 v103, v164, v128, 0
	v_fma_f32 v102, v165, v128, 0
	v_fma_f32 v101, v166, v128, 0
	v_fma_f32 v99, v167, v128, 0
	v_fma_f32 v112, v169, v128, 0
	v_fma_f32 v111, v170, v128, 0
	v_fma_f32 v110, v171, v128, 0
	s_waitcnt lgkmcnt(0)
	v_fma_f32 v106, v128, v172, 0
	v_fma_f32 v105, v128, v173, 0
	v_fma_f32 v104, v128, v174, 0
	v_fma_f32 v100, v128, v175, 0
	v_mul_f32_e32 v97, v97, v115
	v_mul_f32_e32 v97, v35, v97
	s_waitcnt lgkmcnt(0)
	v_fmac_f32_e32 v103, v98, v180
	v_fmac_f32_e32 v113, v98, v176
	v_fmac_f32_e32 v109, v98, v177
	v_fmac_f32_e32 v108, v98, v178
	v_fmac_f32_e32 v107, v98, v179
	v_fmac_f32_e32 v102, v98, v181
	v_fmac_f32_e32 v101, v98, v182
	v_fmac_f32_e32 v99, v98, v183
	s_waitcnt lgkmcnt(0)
	v_fmac_f32_e32 v114, v98, v184
	v_fmac_f32_e32 v112, v98, v185
	v_fmac_f32_e32 v111, v98, v186
	v_fmac_f32_e32 v110, v98, v187
	s_waitcnt lgkmcnt(0)
	v_fmac_f32_e32 v106, v98, v188
	v_fmac_f32_e32 v105, v98, v189
	v_fmac_f32_e32 v104, v98, v190
	v_fmac_f32_e32 v100, v98, v191
	v_cvt_pk_bf16_f32 v98, v97, v5
	global_store_short v[0:1], v98, off offset:256
	v_mul_f32_e32 v96, v96, v115
	v_mul_f32_e32 v96, v36, v96
	s_waitcnt lgkmcnt(0)
	v_fmac_f32_e32 v103, v97, v196
	v_fmac_f32_e32 v113, v97, v192
	v_fmac_f32_e32 v109, v97, v193
	v_fmac_f32_e32 v108, v97, v194
	v_fmac_f32_e32 v107, v97, v195
	v_fmac_f32_e32 v102, v97, v197
	v_fmac_f32_e32 v101, v97, v198
	v_fmac_f32_e32 v99, v97, v199
	s_waitcnt lgkmcnt(0)
	v_fmac_f32_e32 v114, v97, v200
	v_fmac_f32_e32 v112, v97, v201
	v_fmac_f32_e32 v111, v97, v202
	v_fmac_f32_e32 v110, v97, v203
	s_waitcnt lgkmcnt(0)
	v_fmac_f32_e32 v106, v97, v204
	v_fmac_f32_e32 v105, v97, v205
	v_fmac_f32_e32 v104, v97, v206
	v_fmac_f32_e32 v100, v97, v207
	v_cvt_pk_bf16_f32 v97, v96, v5
	global_store_short v[0:1], v97, off offset:384
	v_mul_f32_e32 v95, v95, v115
	v_mul_f32_e32 v95, v37, v95
	s_waitcnt lgkmcnt(0)
	v_fmac_f32_e32 v103, v96, v212
	v_fmac_f32_e32 v113, v96, v208
	v_fmac_f32_e32 v109, v96, v209
	v_fmac_f32_e32 v108, v96, v210
	v_fmac_f32_e32 v107, v96, v211
	v_fmac_f32_e32 v102, v96, v213
	v_fmac_f32_e32 v101, v96, v214
	v_fmac_f32_e32 v99, v96, v215
	s_waitcnt lgkmcnt(0)
	v_fmac_f32_e32 v114, v96, v216
	v_fmac_f32_e32 v112, v96, v217
	v_fmac_f32_e32 v111, v96, v218
	v_fmac_f32_e32 v110, v96, v219
	s_waitcnt lgkmcnt(0)
; #define LAS __attribute__((address_space(3)))
; __device__ __forceinline__ unsigned cvt_pk_bf16(float lo, float hi) { unsigned r; asm volatile("v_cvt_pk_bf16_f32 %0, %1, %2" : "=v"(r) : "v"(lo), "v"(hi)); return r; }
; __device__ __forceinline__ void p0_phase(const Args& a, LAS unsigned char* lds, int tid, int lane, int wave) {
;     ...
;                 for (int j = 0; j < 16; ++j) { const float xn = xa[u][j] * rstd * gm[j];
;                     XN[(size_t)row * D + lane + 64 * j] = (bf16_t)(cvt_pk_bf16(xn, 0.f) & 0xffffu);
;                     const LAS f32x4* wp = (const LAS f32x4*)(wfl + (lane + 64 * j) * 16);
; #pragma unroll
;                     for (int q = 0; q < 4; ++q) { const f32x4 w = wp[q]; f[4 * q + 0] += xn * w[0]; f[4 * q + 1] += xn * w[1]; f[4 * q + 2] += xn * w[2]; f[4 * q + 3] += xn * w[3]; } }
	v_fmac_f32_e32 v106, v96, v220
	v_fmac_f32_e32 v105, v96, v221
	v_fmac_f32_e32 v104, v96, v222
	v_fmac_f32_e32 v100, v96, v223
	v_cvt_pk_bf16_f32 v96, v95, v5
	global_store_short v[0:1], v96, off offset:512
	v_mul_f32_e32 v94, v94, v115
	v_mul_f32_e32 v98, v38, v94
	s_waitcnt lgkmcnt(0)
	v_fmac_f32_e32 v113, v95, v224
	v_cvt_pk_bf16_f32 v116, v98, v5
	global_store_short v[0:1], v116, off offset:640
	v_fmac_f32_e32 v109, v95, v225
	v_fmac_f32_e32 v108, v95, v226
	v_fmac_f32_e32 v107, v95, v227
	s_waitcnt lgkmcnt(0)
	v_fmac_f32_e32 v103, v95, v228
	v_fmac_f32_e32 v102, v95, v229
	v_fmac_f32_e32 v101, v95, v230
	v_fmac_f32_e32 v99, v95, v231
	s_waitcnt lgkmcnt(0)
	v_fmac_f32_e32 v114, v95, v232
	v_fmac_f32_e32 v112, v95, v233
	v_fmac_f32_e32 v111, v95, v234
	v_fmac_f32_e32 v110, v95, v235
	s_waitcnt lgkmcnt(0)
	v_fmac_f32_e32 v106, v95, v236
	v_fmac_f32_e32 v105, v95, v237
	v_fmac_f32_e32 v104, v95, v238
	v_fmac_f32_e32 v100, v95, v239
	ds_read_b128 v[124:127], v69 offset:48
	v_mul_f32_e32 v93, v93, v115
	v_mul_f32_e32 v93, v39, v93
	s_waitcnt lgkmcnt(1)
	v_fmac_f32_e32 v103, v98, v244
	v_fmac_f32_e32 v113, v98, v240
	v_fmac_f32_e32 v109, v98, v241
	v_fmac_f32_e32 v108, v98, v242
	v_fmac_f32_e32 v107, v98, v243
	v_fmac_f32_e32 v102, v98, v245
	v_fmac_f32_e32 v101, v98, v246
	v_fmac_f32_e32 v99, v98, v247
	s_waitcnt lgkmcnt(1)
	v_fmac_f32_e32 v114, v98, v248
	v_fmac_f32_e32 v112, v98, v249
	v_fmac_f32_e32 v111, v98, v250
	v_fmac_f32_e32 v110, v98, v251
	s_waitcnt lgkmcnt(0)
	v_fmac_f32_e32 v106, v98, v124
	v_fmac_f32_e32 v105, v98, v125
	v_fmac_f32_e32 v104, v98, v126
	v_fmac_f32_e32 v100, v98, v127
	v_cvt_pk_bf16_f32 v98, v93, v5
	ds_read_b128 v[94:97], v70
	global_store_short v[0:1], v98, off offset:768
	ds_read_b128 v[116:119], v70 offset:16
	ds_read_b128 v[120:123], v70 offset:32
	ds_read_b128 v[124:127], v70 offset:48
	v_mul_f32_e32 v92, v92, v115
	v_mul_f32_e32 v91, v91, v115
	s_waitcnt lgkmcnt(3)
	v_fmac_f32_e32 v108, v93, v96
	v_fmac_f32_e32 v107, v93, v97
	v_mul_f32_e32 v96, v40, v92
	v_cvt_pk_bf16_f32 v97, v96, v5
	global_store_short v[0:1], v97, off offset:896
	v_fmac_f32_e32 v113, v93, v94
	v_fmac_f32_e32 v109, v93, v95
	s_waitcnt lgkmcnt(2)
	v_fmac_f32_e32 v103, v93, v116
	v_fmac_f32_e32 v102, v93, v117
	v_fmac_f32_e32 v101, v93, v118
	v_fmac_f32_e32 v99, v93, v119
	s_waitcnt lgkmcnt(1)
	v_fmac_f32_e32 v114, v93, v120
	v_fmac_f32_e32 v112, v93, v121
	v_fmac_f32_e32 v111, v93, v122
	v_fmac_f32_e32 v110, v93, v123
	s_waitcnt lgkmcnt(0)
	v_fmac_f32_e32 v106, v93, v124
	v_fmac_f32_e32 v105, v93, v125
	v_fmac_f32_e32 v104, v93, v126
	v_fmac_f32_e32 v100, v93, v127
	ds_read_b128 v[92:95], v71
	ds_read_b128 v[116:119], v71 offset:16
	ds_read_b128 v[120:123], v71 offset:32
	ds_read_b128 v[124:127], v71 offset:48
	v_mul_f32_e32 v91, v41, v91
	v_mul_f32_e32 v90, v90, v115
	s_waitcnt lgkmcnt(2)
	v_fmac_f32_e32 v103, v96, v116
	v_fmac_f32_e32 v113, v96, v92
	v_fmac_f32_e32 v109, v96, v93
	v_fmac_f32_e32 v108, v96, v94
	v_fmac_f32_e32 v107, v96, v95
	v_fmac_f32_e32 v102, v96, v117
	v_fmac_f32_e32 v101, v96, v118
	v_fmac_f32_e32 v99, v96, v119
	s_waitcnt lgkmcnt(1)
	v_fmac_f32_e32 v114, v96, v120
	v_fmac_f32_e32 v112, v96, v121
	v_fmac_f32_e32 v111, v96, v122
	v_fmac_f32_e32 v110, v96, v123
	s_waitcnt lgkmcnt(0)
	v_fmac_f32_e32 v106, v96, v124
	v_fmac_f32_e32 v105, v96, v125
	v_fmac_f32_e32 v104, v96, v126
	v_fmac_f32_e32 v100, v96, v127
	v_cvt_pk_bf16_f32 v96, v91, v5
	ds_read_b128 v[92:95], v72
	global_store_short v[0:1], v96, off offset:1024
	ds_read_b128 v[116:119], v72 offset:16
	ds_read_b128 v[120:123], v72 offset:32
	ds_read_b128 v[124:127], v72 offset:48
	v_mul_f32_e32 v98, v42, v90
	v_mul_f32_e32 v89, v89, v115
	s_waitcnt lgkmcnt(3)
	v_fmac_f32_e32 v108, v91, v94
	v_cvt_pk_bf16_f32 v94, v98, v5
	global_store_short v[0:1], v94, off offset:1152
	v_fmac_f32_e32 v113, v91, v92
	v_fmac_f32_e32 v109, v91, v93
	v_fmac_f32_e32 v107, v91, v95
	s_waitcnt lgkmcnt(2)
	v_fmac_f32_e32 v103, v91, v116
	v_fmac_f32_e32 v102, v91, v117
	v_fmac_f32_e32 v101, v91, v118
	v_fmac_f32_e32 v99, v91, v119
	s_waitcnt lgkmcnt(1)
	v_fmac_f32_e32 v114, v91, v120
	v_fmac_f32_e32 v112, v91, v121
	v_fmac_f32_e32 v111, v91, v122
	v_fmac_f32_e32 v110, v91, v123
	s_waitcnt lgkmcnt(0)
	v_fmac_f32_e32 v106, v91, v124
	v_fmac_f32_e32 v105, v91, v125
	v_fmac_f32_e32 v104, v91, v126
	v_fmac_f32_e32 v100, v91, v127
	ds_read_b128 v[90:93], v73
	ds_read_b128 v[94:97], v73 offset:16
	ds_read_b128 v[116:119], v73 offset:32
	ds_read_b128 v[120:123], v73 offset:48
	v_mul_f32_e32 v89, v43, v89
	v_mul_f32_e32 v88, v88, v115
	s_waitcnt lgkmcnt(2)
	v_fmac_f32_e32 v103, v98, v94
	v_cvt_pk_bf16_f32 v94, v89, v5
	global_store_short v[0:1], v94, off offset:1280
	v_fmac_f32_e32 v113, v98, v90
	v_fmac_f32_e32 v109, v98, v91
	v_fmac_f32_e32 v108, v98, v92
	v_fmac_f32_e32 v107, v98, v93
	v_fmac_f32_e32 v102, v98, v95
	v_fmac_f32_e32 v101, v98, v96
	v_fmac_f32_e32 v99, v98, v97
	s_waitcnt lgkmcnt(1)
	v_fmac_f32_e32 v114, v98, v116
	v_fmac_f32_e32 v112, v98, v117
	v_fmac_f32_e32 v111, v98, v118
	v_fmac_f32_e32 v110, v98, v119
	s_waitcnt lgkmcnt(0)
	v_fmac_f32_e32 v106, v98, v120
	v_fmac_f32_e32 v105, v98, v121
	v_fmac_f32_e32 v104, v98, v122
	v_fmac_f32_e32 v100, v98, v123
	ds_read_b128 v[90:93], v74
	ds_read_b128 v[94:97], v74 offset:16
	ds_read_b128 v[116:119], v74 offset:32
	ds_read_b128 v[120:123], v74 offset:48
	v_mul_f32_e32 v87, v87, v115
	v_mul_f32_e32 v87, v45, v87
	s_waitcnt lgkmcnt(2)
	v_fmac_f32_e32 v103, v89, v94
	v_fmac_f32_e32 v113, v89, v90
	v_fmac_f32_e32 v109, v89, v91
	v_fmac_f32_e32 v108, v89, v92
	v_fmac_f32_e32 v107, v89, v93
	v_fmac_f32_e32 v102, v89, v95
	v_fmac_f32_e32 v101, v89, v96
	v_fmac_f32_e32 v99, v89, v97
	s_waitcnt lgkmcnt(1)
; #define LAS __attribute__((address_space(3)))
; __device__ __forceinline__ unsigned cvt_pk_bf16(float lo, float hi) { unsigned r; asm volatile("v_cvt_pk_bf16_f32 %0, %1, %2" : "=v"(r) : "v"(lo), "v"(hi)); return r; }
; __device__ __forceinline__ void p0_phase(const Args& a, LAS unsigned char* lds, int tid, int lane, int wave) {
;     ...
;                 for (int j = 0; j < 16; ++j) { const float xn = xa[u][j] * rstd * gm[j];
;                     XN[(size_t)row * D + lane + 64 * j] = (bf16_t)(cvt_pk_bf16(xn, 0.f) & 0xffffu);
;                     const LAS f32x4* wp = (const LAS f32x4*)(wfl + (lane + 64 * j) * 16);
; #pragma unroll
;                     for (int q = 0; q < 4; ++q) { const f32x4 w = wp[q]; f[4 * q + 0] += xn * w[0]; f[4 * q + 1] += xn * w[1]; f[4 * q + 2] += xn * w[2]; f[4 * q + 3] += xn * w[3]; } }
;                 { const bool b5 = lane & 32;
; #pragma unroll
;                   for (int k = 0; k < 8; ++k) { const float send = b5 ? f[k] : f[k + 8], keep = b5 ? f[k + 8] : f[k]; f[k] = keep + __shfl_xor(send, 32); }
	v_fmac_f32_e32 v114, v89, v116
	v_fmac_f32_e32 v112, v89, v117
	v_fmac_f32_e32 v111, v89, v118
	v_fmac_f32_e32 v110, v89, v119
	s_waitcnt lgkmcnt(0)
	v_fmac_f32_e32 v106, v89, v120
	v_fmac_f32_e32 v105, v89, v121
	v_fmac_f32_e32 v104, v89, v122
	v_fmac_f32_e32 v100, v89, v123
	v_mul_f32_e32 v96, v44, v88
	v_cvt_pk_bf16_f32 v92, v96, v5
	ds_read_b128 v[88:91], v75
	global_store_short v[0:1], v92, off offset:1408
	ds_read_b128 v[92:95], v75 offset:16
	ds_read_b128 v[116:119], v75 offset:32
	ds_read_b128 v[120:123], v75 offset:48
	v_mul_f32_e32 v86, v86, v115
	v_mul_f32_e32 v98, v46, v86
	s_waitcnt lgkmcnt(3)
	v_fmac_f32_e32 v113, v96, v88
	v_fmac_f32_e32 v109, v96, v89
	v_fmac_f32_e32 v108, v96, v90
	v_fmac_f32_e32 v107, v96, v91
	s_waitcnt lgkmcnt(2)
	v_fmac_f32_e32 v103, v96, v92
	v_cvt_pk_bf16_f32 v92, v87, v5
	ds_read_b128 v[88:91], v76
	global_store_short v[0:1], v92, off offset:1536
	v_fmac_f32_e32 v102, v96, v93
	v_fmac_f32_e32 v101, v96, v94
	v_fmac_f32_e32 v99, v96, v95
	s_waitcnt lgkmcnt(2)
	v_fmac_f32_e32 v114, v96, v116
	v_fmac_f32_e32 v112, v96, v117
	v_fmac_f32_e32 v111, v96, v118
	v_fmac_f32_e32 v110, v96, v119
	s_waitcnt lgkmcnt(1)
	v_fmac_f32_e32 v106, v96, v120
	v_fmac_f32_e32 v105, v96, v121
	v_fmac_f32_e32 v104, v96, v122
	v_fmac_f32_e32 v100, v96, v123
	ds_read_b128 v[92:95], v76 offset:16
	ds_read_b128 v[116:119], v76 offset:32
	ds_read_b128 v[120:123], v76 offset:48
	s_waitcnt lgkmcnt(3)
	v_fmac_f32_e32 v108, v87, v90
	v_cvt_pk_bf16_f32 v90, v98, v5
	global_store_short v[0:1], v90, off offset:1664
	v_fmac_f32_e32 v113, v87, v88
	v_fmac_f32_e32 v109, v87, v89
	v_fmac_f32_e32 v107, v87, v91
	s_waitcnt lgkmcnt(2)
	v_fmac_f32_e32 v103, v87, v92
	v_fmac_f32_e32 v102, v87, v93
	v_fmac_f32_e32 v101, v87, v94
	v_fmac_f32_e32 v99, v87, v95
	s_waitcnt lgkmcnt(1)
	v_fmac_f32_e32 v114, v87, v116
	v_fmac_f32_e32 v112, v87, v117
	v_fmac_f32_e32 v111, v87, v118
	v_fmac_f32_e32 v110, v87, v119
	s_waitcnt lgkmcnt(0)
	v_fmac_f32_e32 v106, v87, v120
	v_fmac_f32_e32 v105, v87, v121
	v_fmac_f32_e32 v104, v87, v122
	v_fmac_f32_e32 v100, v87, v123
	ds_read_b128 v[86:89], v77
	ds_read_b128 v[90:93], v77 offset:16
	ds_read_b128 v[94:97], v77 offset:32
	ds_read_b128 v[116:119], v77 offset:48
	v_mul_f32_e32 v85, v85, v115
	v_mul_f32_e32 v84, v84, v115
	s_waitcnt lgkmcnt(2)
	v_fmac_f32_e32 v103, v98, v90
	v_fmac_f32_e32 v113, v98, v86
	v_fmac_f32_e32 v109, v98, v87
	v_fmac_f32_e32 v108, v98, v88
	v_fmac_f32_e32 v107, v98, v89
	v_fmac_f32_e32 v102, v98, v91
	v_fmac_f32_e32 v101, v98, v92
	v_fmac_f32_e32 v99, v98, v93
	s_waitcnt lgkmcnt(1)
	v_fmac_f32_e32 v114, v98, v94
	v_fmac_f32_e32 v112, v98, v95
	v_fmac_f32_e32 v111, v98, v96
	v_fmac_f32_e32 v110, v98, v97
	s_waitcnt lgkmcnt(0)
	v_fmac_f32_e32 v106, v98, v116
	v_fmac_f32_e32 v105, v98, v117
	v_fmac_f32_e32 v104, v98, v118
	v_fmac_f32_e32 v100, v98, v119
	v_mul_f32_e32 v98, v47, v85
	v_cvt_pk_bf16_f32 v85, v98, v5
	ds_read_b128 v[86:89], v78
	global_store_short v[0:1], v85, off offset:1792
	ds_read_b128 v[90:93], v78 offset:16
	ds_read_b128 v[94:97], v78 offset:32
	ds_read_b128 v[116:119], v78 offset:48
	s_waitcnt lgkmcnt(3)
	v_fmac_f32_e32 v113, v98, v86
	v_fmac_f32_e32 v109, v98, v87
	s_waitcnt lgkmcnt(1)
	v_fmac_f32_e32 v111, v98, v96
	v_fmac_f32_e32 v110, v98, v97
	v_mul_f32_e32 v96, v48, v84
	v_cvt_pk_bf16_f32 v97, v96, v5
	ds_read_b128 v[84:87], v79
	v_fmac_f32_e32 v108, v98, v88
	v_fmac_f32_e32 v107, v98, v89
	v_fmac_f32_e32 v103, v98, v90
	v_fmac_f32_e32 v102, v98, v91
	v_fmac_f32_e32 v101, v98, v92
	v_fmac_f32_e32 v99, v98, v93
	v_fmac_f32_e32 v114, v98, v94
	v_fmac_f32_e32 v112, v98, v95
	s_waitcnt lgkmcnt(1)
	v_fmac_f32_e32 v106, v98, v116
	v_fmac_f32_e32 v105, v98, v117
	v_fmac_f32_e32 v104, v98, v118
	v_fmac_f32_e32 v100, v98, v119
	ds_read_b128 v[88:91], v79 offset:16
	ds_read_b128 v[92:95], v79 offset:32
	ds_read_b128 v[116:119], v79 offset:48
	s_waitcnt lgkmcnt(3)
	v_fmac_f32_e32 v113, v96, v84
	v_fmac_f32_e32 v109, v96, v85
	v_fmac_f32_e32 v108, v96, v86
	s_waitcnt lgkmcnt(1)
	v_fmac_f32_e32 v114, v96, v92
	v_fmac_f32_e32 v112, v96, v93
	v_cndmask_b32_e64 v84, v113, v114, s[26:27]
	v_fmac_f32_e32 v111, v96, v94
	v_mov_b32_e32 v253, v84
	s_nop 1
	v_permlane32_swap_b32_e32 v84, v253
	v_cndmask_b32_e64 v84, v84, v253, s[26:27]
	v_cndmask_b32_e64 v86, v109, v112, s[26:27]
	v_fmac_f32_e32 v107, v96, v87
	v_mov_b32_e32 v253, v86
	s_nop 1
	v_permlane32_swap_b32_e32 v86, v253
	v_cndmask_b32_e64 v86, v86, v253, s[26:27]
	v_cndmask_b32_e64 v87, v108, v111, s[26:27]
	v_mov_b32_e32 v253, v87
	s_nop 1
	v_permlane32_swap_b32_e32 v87, v253
	v_cndmask_b32_e64 v87, v87, v253, s[26:27]
	v_cndmask_b32_e64 v85, v114, v113, s[26:27]
	s_waitcnt lgkmcnt(0)
	v_add_f32_e32 v84, v85, v84
	v_cndmask_b32_e64 v85, v112, v109, s[26:27]
	v_fmac_f32_e32 v110, v96, v95
	s_waitcnt lgkmcnt(0)
	v_add_f32_e32 v85, v85, v86
	v_cndmask_b32_e64 v86, v111, v108, s[26:27]
	v_fmac_f32_e32 v103, v96, v88
	v_fmac_f32_e32 v106, v96, v116
	s_waitcnt lgkmcnt(0)
	v_add_f32_e32 v86, v86, v87
	v_cndmask_b32_e64 v87, v107, v110, s[26:27]
	v_fmac_f32_e32 v102, v96, v89
	v_fmac_f32_e32 v105, v96, v117
	v_mov_b32_e32 v253, v87
	s_nop 1
	v_permlane32_swap_b32_e32 v87, v253
	v_cndmask_b32_e64 v87, v87, v253, s[26:27]
	v_cndmask_b32_e64 v89, v103, v106, s[26:27]
	v_fmac_f32_e32 v101, v96, v90
	v_mov_b32_e32 v253, v89
	s_nop 1
	v_permlane32_swap_b32_e32 v89, v253
	v_cndmask_b32_e64 v89, v89, v253, s[26:27]
	v_cndmask_b32_e64 v90, v102, v105, s[26:27]
	v_mov_b32_e32 v253, v90
	s_nop 1
	v_permlane32_swap_b32_e32 v90, v253
	v_cndmask_b32_e64 v90, v90, v253, s[26:27]
	v_cndmask_b32_e64 v88, v110, v107, s[26:27]
	s_waitcnt lgkmcnt(0)
; __device__ __forceinline__ void p0_phase(const Args& a, LAS unsigned char* lds, int tid, int lane, int wave) {
;     ...
;                 { const bool b5 = lane & 32;
; #pragma unroll
;                   for (int k = 0; k < 8; ++k) { const float send = b5 ? f[k] : f[k + 8], keep = b5 ? f[k + 8] : f[k]; f[k] = keep + __shfl_xor(send, 32); }
;                   const bool b4 = lane & 16;
; #pragma unroll
;                   for (int k = 0; k < 4; ++k) { const float send = b4 ? f[k] : f[k + 4], keep = b4 ? f[k + 4] : f[k]; f[k] = keep + __shfl_xor(send, 16); }
;                   const bool b3 = lane & 8;
; #pragma unroll
;                   for (int k = 0; k < 2; ++k) { const float send = b3 ? f[k] : f[k + 2], keep = b3 ? f[k + 2] : f[k]; f[k] = keep + __shfl_xor(send, 8); }
;                   const bool b2 = lane & 4;
;                   { const float send = b2 ? f[0] : f[1], keep = b2 ? f[1] : f[0]; f[0] = keep + __shfl_xor(send, 4); }
;                   f[0] += __shfl_xor(f[0], 2); f[0] += __shfl_xor(f[0], 1); }
;                 if ((lane & 3) == 0) { const int hh = ((lane >> 5) & 1) * 8 + ((lane >> 4) & 1) * 4 + ((lane >> 3) & 1) * 2 + ((lane >> 2) & 1);
;                     const float z = f[0] + bfg[hh]; const float lg = fminf(z, 0.f) - log1pf(expf(-fabsf(z)));
;                     lf[rl * 16 + hh] = lg;
;                     if (row < MP) a.out[O_LFP + (size_t)row * NH + hh] = lg; else a.out[O_LFS + (size_t)(row - MP) * NH + hh] = lg; }
	v_add_f32_e32 v87, v88, v87
	v_cndmask_b32_e64 v88, v106, v103, s[26:27]
	v_fmac_f32_e32 v104, v96, v118
	s_waitcnt lgkmcnt(0)
	v_add_f32_e32 v88, v88, v89
	v_cndmask_b32_e64 v89, v105, v102, s[26:27]
	v_fmac_f32_e32 v99, v96, v91
	v_fmac_f32_e32 v100, v96, v119
	s_waitcnt lgkmcnt(0)
	v_add_f32_e32 v89, v89, v90
	v_cndmask_b32_e64 v90, v101, v104, s[26:27]
	v_mov_b32_e32 v253, v90
	s_nop 1
	v_permlane32_swap_b32_e32 v90, v253
	v_cndmask_b32_e64 v90, v90, v253, s[26:27]
	v_cndmask_b32_e64 v92, v99, v100, s[26:27]
	v_mov_b32_e32 v253, v92
	s_nop 1
	v_permlane32_swap_b32_e32 v92, v253
	v_cndmask_b32_e64 v92, v92, v253, s[26:27]
	v_cndmask_b32_e64 v91, v104, v101, s[26:27]
	v_cndmask_b32_e64 v93, v84, v88, s[28:29]
	s_waitcnt lgkmcnt(0)
	v_add_f32_e32 v90, v91, v90
	v_cndmask_b32_e64 v91, v100, v99, s[26:27]
	s_waitcnt lgkmcnt(0)
	v_add_f32_e32 v91, v91, v92
	v_cndmask_b32_e64 v84, v88, v84, s[28:29]
	v_cndmask_b32_e64 v88, v85, v89, s[28:29]
	v_cndmask_b32_e64 v85, v89, v85, s[28:29]
	v_cndmask_b32_e64 v89, v86, v90, s[28:29]
	v_cndmask_b32_e64 v92, v87, v91, s[28:29]
	v_mov_b32_e32 v253, v93
	s_nop 1
	v_permlane16_swap_b32_e32 v93, v253
	v_cndmask_b32_e64 v93, v93, v253, s[28:29]
	v_mov_b32_e32 v253, v88
	s_nop 1
	v_permlane16_swap_b32_e32 v88, v253
	v_cndmask_b32_e64 v88, v88, v253, s[28:29]
	v_mov_b32_e32 v253, v89
	s_nop 1
	v_permlane16_swap_b32_e32 v89, v253
	v_cndmask_b32_e64 v89, v89, v253, s[28:29]
	v_mov_b32_e32 v253, v92
	s_nop 1
	v_permlane16_swap_b32_e32 v92, v253
	v_cndmask_b32_e64 v92, v92, v253, s[28:29]
	v_cndmask_b32_e64 v86, v90, v86, s[28:29]
	v_cndmask_b32_e64 v87, v91, v87, s[28:29]
	s_waitcnt lgkmcnt(0)
	v_add_f32_e32 v84, v84, v93
	s_waitcnt lgkmcnt(0)
	v_add_f32_e32 v85, v85, v88
	s_waitcnt lgkmcnt(0)
	v_add_f32_e32 v86, v86, v89
	s_waitcnt lgkmcnt(0)
	v_add_f32_e32 v87, v87, v92
	v_cndmask_b32_e64 v88, v84, v86, s[30:31]
	v_cndmask_b32_e64 v89, v85, v87, s[30:31]
	s_nop 1
	v_mov_b32_dpp v88, v88 row_ror:8 row_mask:0xf bank_mask:0xf
	s_nop 1
	v_mov_b32_dpp v89, v89 row_ror:8 row_mask:0xf bank_mask:0xf
	v_cndmask_b32_e64 v84, v86, v84, s[30:31]
	v_cndmask_b32_e64 v85, v87, v85, s[30:31]
	global_store_short v[0:1], v97, off offset:1920
	s_waitcnt lgkmcnt(0)
	v_add_f32_e32 v84, v84, v88
	s_waitcnt lgkmcnt(0)
	v_add_f32_e32 v85, v85, v89
	v_cndmask_b32_e64 v86, v84, v85, s[34:35]
	v_mov_b32_e32 v253, v86
	s_nop 1
	v_mov_b32_dpp v86, v253 row_shl:4 row_mask:0xf bank_mask:0x5
	s_nop 1
	v_mov_b32_dpp v86, v253 row_shr:4 row_mask:0xf bank_mask:0xa
	v_cndmask_b32_e64 v84, v85, v84, s[34:35]
	s_waitcnt lgkmcnt(0)
	v_add_f32_e32 v84, v84, v86
	s_nop 1
	v_mov_b32_dpp v85, v84 quad_perm:[2,3,0,1] row_mask:0xf bank_mask:0xf
	s_waitcnt lgkmcnt(0)
	v_add_f32_e32 v84, v84, v85
	s_nop 1
	v_mov_b32_dpp v85, v84 quad_perm:[1,0,3,2] row_mask:0xf bank_mask:0xf
	s_and_saveexec_b64 s[0:1], s[36:37]
	s_cbranch_execz .LBB0_39
	global_load_dword v0, v[10:11], off
	s_waitcnt lgkmcnt(0)
	v_add_f32_e32 v1, v84, v85
	v_lshl_add_u32 v84, s11, 6, v51
	s_add_i32 s11, s92, 0xffffc000
	s_cmpk_lt_i32 s92, 0x4000
	s_cselect_b32 s13, s93, 0
	s_cselect_b32 s12, s92, s11
	s_cselect_b32 s11, s7, 0xcd04000
	s_lshl_b64 s[12:13], s[12:13], 6
	s_add_u32 s12, s86, s12
	s_addc_u32 s13, s87, s13
	s_add_u32 s92, s12, s11
	s_addc_u32 s93, s13, 0
	s_waitcnt vmcnt(0)
	v_add_f32_e32 v0, v1, v0
	v_mul_f32_e64 v1, |v0|, s70
	v_fma_f32 v85, |v0|, s70, -v1
	v_rndne_f32_e32 v86, v1
	v_fma_f32 v85, |v0|, s71, v85
	v_sub_f32_e32 v1, v1, v86
	v_add_f32_e32 v1, v1, v85
	v_cvt_i32_f32_e32 v86, v86
	v_exp_f32_e32 v1, v1
	v_cmp_ngt_f32_e64 vcc, |v0|, s50
	v_min_f32_e32 v85, 0, v0
	v_ldexp_f32 v1, v1, v86
	v_cndmask_b32_e32 v1, 0, v1, vcc
	v_cmp_nlt_f32_e64 vcc, |v0|, s94
	s_nop 1
	v_cndmask_b32_e32 v86, v63, v1, vcc
	v_add_f32_e32 v87, 1.0, v86
	v_add_f32_e32 v88, -1.0, v87
	v_frexp_mant_f32_e32 v89, v87
	v_cvt_f64_f32_e32 v[0:1], v87
	v_sub_f32_e32 v90, v88, v87
	v_frexp_exp_i32_f64_e32 v0, v[0:1]
	v_cmp_gt_f32_e32 vcc, s4, v89
	v_sub_f32_e32 v88, v86, v88
	v_add_f32_e32 v1, 1.0, v90
	v_subbrev_co_u32_e32 v0, vcc, 0, v0, vcc
	v_add_f32_e32 v1, v88, v1
	v_sub_u32_e32 v88, 0, v0
	v_cvt_f32_i32_e32 v0, v0
	v_ldexp_f32 v87, v87, v88
	v_ldexp_f32 v1, v1, v88
	v_add_f32_e32 v88, -1.0, v87
	v_add_f32_e32 v89, 1.0, v87
	v_add_f32_e32 v90, 1.0, v88
	v_add_f32_e32 v91, -1.0, v89
	v_sub_f32_e32 v90, v87, v90
	v_sub_f32_e32 v87, v87, v91
	v_mul_f32_e32 v91, 0x3f317218, v0
	v_add_f32_e32 v90, v1, v90
	v_add_f32_e32 v1, v1, v87
	v_fma_f32 v87, v0, s5, -v91
	v_add_f32_e32 v92, v88, v90
	v_add_f32_e32 v93, v89, v1
	v_fmac_f32_e32 v87, 0xb102e308, v0
	v_sub_f32_e32 v0, v88, v92
	v_sub_f32_e32 v88, v89, v93
	v_rcp_f32_e32 v89, v93
	v_add_f32_e32 v94, v91, v87
	v_add_f32_e32 v1, v1, v88
	v_sub_f32_e32 v88, v94, v91
	v_sub_f32_e32 v87, v87, v88
	v_mul_f32_e32 v88, v92, v89
	v_add_f32_e32 v0, v90, v0
	v_mul_f32_e32 v90, v93, v88
	v_fma_f32 v91, v88, v93, -v90
	v_fmac_f32_e32 v91, v88, v1
	v_add_f32_e32 v95, v90, v91
	v_sub_f32_e32 v96, v92, v95
	v_sub_f32_e32 v90, v95, v90
	v_sub_f32_e32 v92, v92, v96
	v_sub_f32_e32 v90, v90, v91
	v_sub_f32_e32 v91, v92, v95
	v_add_f32_e32 v0, v0, v91
	v_add_f32_e32 v0, v90, v0
	v_add_f32_e32 v90, v96, v0
	v_mul_f32_e32 v91, v89, v90
	v_sub_f32_e32 v92, v96, v90
	v_mul_f32_e32 v95, v93, v91
	v_add_f32_e32 v0, v0, v92
	v_add_f32_e32 v92, v88, v91
	v_fma_f32 v93, v91, v93, -v95
	v_sub_f32_e32 v88, v92, v88
	v_fmac_f32_e32 v93, v91, v1
	v_sub_f32_e32 v1, v91, v88
	v_add_f32_e32 v88, v95, v93
	v_sub_f32_e32 v91, v88, v95
	v_sub_f32_e32 v95, v90, v88
	v_sub_f32_e32 v90, v90, v95
	v_sub_f32_e32 v88, v90, v88
	v_sub_f32_e32 v91, v91, v93
	v_add_f32_e32 v0, v0, v88
	v_add_f32_e32 v0, v91, v0
	v_add_f32_e32 v0, v95, v0
	v_mul_f32_e32 v0, v89, v0
	v_add_f32_e32 v0, v1, v0
	v_add_f32_e32 v1, v92, v0
	v_mul_f32_e32 v88, v1, v1
	v_fmamk_f32 v91, v88, 0x3e9b6dac, v62
	v_sub_f32_e32 v89, v1, v92
	v_ldexp_f32 v90, v1, 1
	v_mul_f32_e32 v1, v1, v88
	v_fmaak_f32 v88, v88, v91, 0x3f2aaada
	v_mul_f32_e32 v1, v1, v88
	v_add_f32_e32 v88, v90, v1
	v_sub_f32_e32 v0, v0, v89
	v_sub_f32_e32 v89, v88, v90
	v_ldexp_f32 v0, v0, 1
	v_sub_f32_e32 v1, v1, v89
	v_add_f32_e32 v0, v0, v1
	v_add_f32_e32 v1, v88, v0
	v_sub_f32_e32 v88, v1, v88
	v_add_f32_e32 v89, v94, v1
	v_sub_f32_e32 v0, v0, v88
	v_sub_f32_e32 v88, v89, v94
	v_sub_f32_e32 v90, v89, v88
	v_sub_f32_e32 v1, v1, v88
	v_add_f32_e32 v88, v87, v0
	v_sub_f32_e32 v90, v94, v90
	v_sub_f32_e32 v91, v88, v87
	v_add_f32_e32 v1, v1, v90
	v_sub_f32_e32 v90, v88, v91
	v_sub_f32_e32 v0, v0, v91
	v_sub_f32_e32 v87, v87, v90
	v_add_f32_e32 v1, v88, v1
	v_add_f32_e32 v0, v0, v87
	v_add_f32_e32 v87, v89, v1
	v_sub_f32_e32 v88, v87, v89
	v_sub_f32_e32 v1, v1, v88
	v_add_f32_e32 v0, v0, v1
	v_add_f32_e32 v0, v87, v0
	v_cmp_neq_f32_e32 vcc, s95, v86
	s_nop 1
	v_cndmask_b32_e32 v0, v63, v0, vcc
	v_cmp_lt_f32_e64 vcc, |v86|, s6
	s_nop 1
	v_cndmask_b32_e32 v0, v0, v86, vcc
	v_sub_f32_e32 v0, v85, v0
	ds_write_b32 v84, v0
	global_store_dword v33, v0, s[92:93]
; #define LAS __attribute__((address_space(3)))
; __device__ __forceinline__ unsigned cvt_pk_bf16(float lo, float hi) { unsigned r; asm volatile("v_cvt_pk_bf16_f32 %0, %1, %2" : "=v"(r) : "v"(lo), "v"(hi)); return r; }
; __device__ __forceinline__ void p0_phase(const Args& a, LAS unsigned char* lds, int tid, int lane, int wave) {
;     ...
;                 for (int u = 0; u < 4; ++u) {
;                 const int rl = wave * 8 + i4 * 4 + u, row = c * 64 + rl;
;                 float ss = 0.f;
; #pragma unroll
;                 for (int j = 0; j < 16; ++j) ss += xa[u][j] * xa[u][j];
;                 const float rstd = 1.0f / sqrtf(wave_sum(ss) * (1.f / D) + EPS);
;                 float f[16];
; #pragma unroll
;                 for (int h = 0; h < 16; ++h) f[h] = 0.f;
; #pragma unroll
;                 for (int j = 0; j < 16; ++j) { const float xn = xa[u][j] * rstd * gm[j];
;                     XN[(size_t)row * D + lane + 64 * j] = (bf16_t)(cvt_pk_bf16(xn, 0.f) & 0xffffu);
;                     const LAS f32x4* wp = (const LAS f32x4*)(wfl + (lane + 64 * j) * 16);
; #pragma unroll
;                     for (int q = 0; q < 4; ++q) { const f32x4 w = wp[q]; f[4 * q + 0] += xn * w[0]; f[4 * q + 1] += xn * w[1]; f[4 * q + 2] += xn * w[2]; f[4 * q + 3] += xn * w[3]; } }
.LBB0_39:
	s_or_b64 exec, exec, s[0:1]
	s_waitcnt vmcnt(61)
	v_mul_f32_e32 v0, v81, v81
	v_fmac_f32_e32 v0, v82, v82
	s_waitcnt vmcnt(60)
	v_fmac_f32_e32 v0, v80, v80
	s_waitcnt vmcnt(59)
	v_fmac_f32_e32 v0, v32, v32
	s_waitcnt vmcnt(58)
	v_fmac_f32_e32 v0, v31, v31
	s_waitcnt vmcnt(57)
	v_fmac_f32_e32 v0, v30, v30
	s_waitcnt vmcnt(56)
	v_fmac_f32_e32 v0, v29, v29
	s_waitcnt vmcnt(55)
	v_fmac_f32_e32 v0, v28, v28
	s_waitcnt vmcnt(54)
	v_fmac_f32_e32 v0, v27, v27
	s_waitcnt vmcnt(53)
	v_fmac_f32_e32 v0, v26, v26
	s_waitcnt vmcnt(52)
	v_fmac_f32_e32 v0, v25, v25
	s_waitcnt vmcnt(51)
	v_fmac_f32_e32 v0, v24, v24
	s_waitcnt vmcnt(50)
	v_fmac_f32_e32 v0, v23, v23
	s_waitcnt vmcnt(49)
	v_fmac_f32_e32 v0, v22, v22
	s_waitcnt vmcnt(48)
	v_fmac_f32_e32 v0, v21, v21
	v_fmac_f32_e32 v0, v20, v20
	s_nop 1
	v_mov_b32_dpp v1, v0 quad_perm:[1,0,3,2] row_mask:0xf bank_mask:0xf
	s_or_b32 s10, s10, 3
	s_add_i32 s92, s10, s45
	s_ashr_i32 s93, s92, 31
	s_lshl_b64 s[12:13], s[92:93], 11
	s_waitcnt lgkmcnt(0)
	v_add_f32_e32 v0, v0, v1
	s_nop 1
	v_mov_b32_dpp v1, v0 quad_perm:[2,3,0,1] row_mask:0xf bank_mask:0xf
	s_waitcnt lgkmcnt(0)
	v_add_f32_e32 v0, v0, v1
	s_nop 1
	v_mov_b32_dpp v1, v0 row_shl:4 row_mask:0xf bank_mask:0x5
	s_nop 1
	v_mov_b32_dpp v1, v0 row_shr:4 row_mask:0xf bank_mask:0xa
	s_waitcnt lgkmcnt(0)
	v_add_f32_e32 v0, v0, v1
	s_nop 1
	v_mov_b32_dpp v1, v0 row_ror:8 row_mask:0xf bank_mask:0xf
	s_waitcnt lgkmcnt(0)
	v_add_f32_e32 v0, v0, v1
	v_mov_b32_e32 v1, v0
	v_mov_b32_e32 v253, v0
	s_nop 1
	v_permlane16_swap_b32_e32 v1, v253
	v_cndmask_b32_e64 v1, v1, v253, s[28:29]
	s_waitcnt lgkmcnt(0)
	v_add_f32_e32 v0, v0, v1
	v_mov_b32_e32 v1, v0
	v_mov_b32_e32 v253, v0
	s_nop 1
	v_permlane32_swap_b32_e32 v1, v253
	v_cndmask_b32_e64 v1, v1, v253, s[26:27]
	s_waitcnt lgkmcnt(0)
	v_add_f32_e32 v0, v0, v1
	v_fmamk_f32 v0, v0, 0x3a800000, v60
	v_mul_f32_e32 v1, 0x4f800000, v0
	v_cmp_gt_f32_e32 vcc, s49, v0
	s_nop 1
	v_cndmask_b32_e32 v0, v0, v1, vcc
	v_sqrt_f32_e32 v1, v0
	s_nop 0
	v_add_u32_e32 v84, -1, v1
	v_add_u32_e32 v85, 1, v1
	v_fma_f32 v86, -v84, v1, v0
	v_fma_f32 v87, -v85, v1, v0
	v_cmp_ge_f32_e64 s[0:1], 0, v86
	s_nop 1
	v_cndmask_b32_e64 v1, v1, v84, s[0:1]
	v_cmp_lt_f32_e64 s[0:1], 0, v87
	s_nop 1
	v_cndmask_b32_e64 v1, v1, v85, s[0:1]
	v_mul_f32_e32 v84, 0x37800000, v1
	v_cndmask_b32_e32 v1, v1, v84, vcc
	v_cmp_class_f32_e32 vcc, v0, v61
	s_nop 1
	v_cndmask_b32_e32 v84, v1, v0, vcc
	v_div_scale_f32 v85, s[0:1], v84, v84, 1.0
	v_rcp_f32_e32 v86, v85
	v_div_scale_f32 v87, vcc, 1.0, v84, 1.0
	v_lshl_add_u64 v[0:1], v[6:7], 0, s[12:13]
	v_fma_f32 v88, -v85, v86, 1.0
	v_fmac_f32_e32 v86, v88, v86
	v_mul_f32_e32 v88, v87, v86
	v_fma_f32 v89, -v85, v88, v87
	v_fmac_f32_e32 v88, v89, v86
	v_fma_f32 v85, -v85, v88, v87
	v_div_fmas_f32 v85, v85, v86, v88
	v_div_fixup_f32 v98, v85, v84, 1.0
	v_mul_f32_e32 v82, v82, v98
	v_mul_f32_e32 v99, v9, v82
	v_cvt_pk_bf16_f32 v82, v99, v5
	v_mul_f32_e32 v81, v81, v98
	global_store_short v[0:1], v82, off
	s_waitcnt lgkmcnt(0)
	v_fma_f32 v96, v160, v99, 0
	v_fma_f32 v92, v161, v99, 0
	v_fma_f32 v91, v162, v99, 0
	v_fma_f32 v90, v163, v99, 0
	s_waitcnt lgkmcnt(0)
	v_fma_f32 v86, v164, v99, 0
	v_fma_f32 v85, v165, v99, 0
	v_fma_f32 v84, v166, v99, 0
	v_fma_f32 v82, v167, v99, 0
	s_waitcnt lgkmcnt(0)
	v_fma_f32 v97, v168, v99, 0
	v_fma_f32 v95, v169, v99, 0
	v_fma_f32 v94, v170, v99, 0
	v_fma_f32 v93, v171, v99, 0
	s_waitcnt lgkmcnt(0)
	v_fma_f32 v89, v99, v172, 0
	v_fma_f32 v88, v99, v173, 0
	v_fma_f32 v87, v99, v174, 0
	v_fma_f32 v83, v99, v175, 0
	v_mul_f32_e32 v81, v34, v81
	v_cvt_pk_bf16_f32 v99, v81, v5
	global_store_short v[0:1], v99, off offset:128
	v_mul_f32_e32 v80, v80, v98
	v_mul_f32_e32 v80, v35, v80
	s_waitcnt lgkmcnt(0)
	v_fmac_f32_e32 v86, v81, v180
	v_fmac_f32_e32 v96, v81, v176
	v_fmac_f32_e32 v92, v81, v177
	v_fmac_f32_e32 v91, v81, v178
	v_fmac_f32_e32 v90, v81, v179
	v_fmac_f32_e32 v85, v81, v181
	v_fmac_f32_e32 v84, v81, v182
	v_fmac_f32_e32 v82, v81, v183
	s_waitcnt lgkmcnt(0)
	v_fmac_f32_e32 v97, v81, v184
	v_fmac_f32_e32 v95, v81, v185
	v_fmac_f32_e32 v94, v81, v186
	v_fmac_f32_e32 v93, v81, v187
	s_waitcnt lgkmcnt(0)
	v_fmac_f32_e32 v89, v81, v188
	v_fmac_f32_e32 v88, v81, v189
	v_fmac_f32_e32 v87, v81, v190
	v_fmac_f32_e32 v83, v81, v191
	v_cvt_pk_bf16_f32 v81, v80, v5
	global_store_short v[0:1], v81, off offset:256
	v_mul_f32_e32 v32, v32, v98
	v_mul_f32_e32 v32, v36, v32
	s_waitcnt lgkmcnt(0)
	v_fmac_f32_e32 v86, v80, v196
	v_fmac_f32_e32 v96, v80, v192
	v_fmac_f32_e32 v92, v80, v193
	v_fmac_f32_e32 v91, v80, v194
	v_fmac_f32_e32 v90, v80, v195
	v_fmac_f32_e32 v85, v80, v197
	v_fmac_f32_e32 v84, v80, v198
	v_fmac_f32_e32 v82, v80, v199
	s_waitcnt lgkmcnt(0)
	v_fmac_f32_e32 v97, v80, v200
	v_fmac_f32_e32 v95, v80, v201
	v_fmac_f32_e32 v94, v80, v202
	v_fmac_f32_e32 v93, v80, v203
	s_waitcnt lgkmcnt(0)
	v_fmac_f32_e32 v89, v80, v204
	v_fmac_f32_e32 v88, v80, v205
	v_fmac_f32_e32 v87, v80, v206
	v_fmac_f32_e32 v83, v80, v207
	v_cvt_pk_bf16_f32 v80, v32, v5
	global_store_short v[0:1], v80, off offset:384
	v_mul_f32_e32 v31, v31, v98
	v_mul_f32_e32 v31, v37, v31
	s_waitcnt lgkmcnt(0)
	v_fmac_f32_e32 v86, v32, v212
	v_fmac_f32_e32 v96, v32, v208
	v_fmac_f32_e32 v92, v32, v209
	v_fmac_f32_e32 v91, v32, v210
	v_fmac_f32_e32 v90, v32, v211
	v_fmac_f32_e32 v85, v32, v213
	v_fmac_f32_e32 v84, v32, v214
	v_fmac_f32_e32 v82, v32, v215
	s_waitcnt lgkmcnt(0)
	v_fmac_f32_e32 v97, v32, v216
	v_fmac_f32_e32 v95, v32, v217
	v_fmac_f32_e32 v94, v32, v218
	v_fmac_f32_e32 v93, v32, v219
	s_waitcnt lgkmcnt(0)
; #define LAS __attribute__((address_space(3)))
; __device__ __forceinline__ unsigned cvt_pk_bf16(float lo, float hi) { unsigned r; asm volatile("v_cvt_pk_bf16_f32 %0, %1, %2" : "=v"(r) : "v"(lo), "v"(hi)); return r; }
; __device__ __forceinline__ void p0_phase(const Args& a, LAS unsigned char* lds, int tid, int lane, int wave) {
;     ...
;                 for (int j = 0; j < 16; ++j) { const float xn = xa[u][j] * rstd * gm[j];
;                     XN[(size_t)row * D + lane + 64 * j] = (bf16_t)(cvt_pk_bf16(xn, 0.f) & 0xffffu);
;                     const LAS f32x4* wp = (const LAS f32x4*)(wfl + (lane + 64 * j) * 16);
; #pragma unroll
;                     for (int q = 0; q < 4; ++q) { const f32x4 w = wp[q]; f[4 * q + 0] += xn * w[0]; f[4 * q + 1] += xn * w[1]; f[4 * q + 2] += xn * w[2]; f[4 * q + 3] += xn * w[3]; } }
	v_fmac_f32_e32 v89, v32, v220
	v_fmac_f32_e32 v88, v32, v221
	v_fmac_f32_e32 v87, v32, v222
	v_fmac_f32_e32 v83, v32, v223
	v_cvt_pk_bf16_f32 v32, v31, v5
	global_store_short v[0:1], v32, off offset:512
	v_mul_f32_e32 v30, v30, v98
	v_mul_f32_e32 v30, v38, v30
	s_waitcnt lgkmcnt(0)
	v_fmac_f32_e32 v86, v31, v228
	v_fmac_f32_e32 v96, v31, v224
	v_fmac_f32_e32 v92, v31, v225
	v_fmac_f32_e32 v91, v31, v226
	v_fmac_f32_e32 v90, v31, v227
	v_fmac_f32_e32 v85, v31, v229
	v_fmac_f32_e32 v84, v31, v230
	v_fmac_f32_e32 v82, v31, v231
	s_waitcnt lgkmcnt(0)
	v_fmac_f32_e32 v97, v31, v232
	v_fmac_f32_e32 v95, v31, v233
	v_fmac_f32_e32 v94, v31, v234
	v_fmac_f32_e32 v93, v31, v235
	s_waitcnt lgkmcnt(0)
	v_fmac_f32_e32 v89, v31, v236
	v_fmac_f32_e32 v88, v31, v237
	v_fmac_f32_e32 v87, v31, v238
	v_fmac_f32_e32 v83, v31, v239
	v_cvt_pk_bf16_f32 v31, v30, v5
	global_store_short v[0:1], v31, off offset:640
	ds_read_b128 v[112:115], v69 offset:48
	v_mul_f32_e32 v29, v29, v98
	v_mul_f32_e32 v29, v39, v29
	s_waitcnt lgkmcnt(1)
	v_fmac_f32_e32 v86, v30, v244
	v_fmac_f32_e32 v96, v30, v240
	v_fmac_f32_e32 v92, v30, v241
	v_fmac_f32_e32 v91, v30, v242
	v_fmac_f32_e32 v90, v30, v243
	v_fmac_f32_e32 v85, v30, v245
	v_fmac_f32_e32 v84, v30, v246
	v_fmac_f32_e32 v82, v30, v247
	s_waitcnt lgkmcnt(1)
	v_fmac_f32_e32 v97, v30, v248
	v_fmac_f32_e32 v95, v30, v249
	v_fmac_f32_e32 v94, v30, v250
	v_fmac_f32_e32 v93, v30, v251
	s_waitcnt lgkmcnt(0)
	v_fmac_f32_e32 v89, v30, v112
	v_fmac_f32_e32 v88, v30, v113
	v_fmac_f32_e32 v87, v30, v114
	v_fmac_f32_e32 v83, v30, v115
	v_cvt_pk_bf16_f32 v30, v29, v5
	global_store_short v[0:1], v30, off offset:768
	ds_read_b128 v[100:103], v70
	ds_read_b128 v[104:107], v70 offset:16
	ds_read_b128 v[108:111], v70 offset:32
	ds_read_b128 v[112:115], v70 offset:48
	v_mul_f32_e32 v28, v28, v98
	v_mul_f32_e32 v32, v40, v28
	v_cvt_pk_bf16_f32 v80, v32, v5
	global_store_short v[0:1], v80, off offset:896
	s_waitcnt lgkmcnt(3)
	v_fmac_f32_e32 v96, v29, v100
	v_fmac_f32_e32 v92, v29, v101
	v_fmac_f32_e32 v91, v29, v102
	v_fmac_f32_e32 v90, v29, v103
	s_waitcnt lgkmcnt(2)
	v_fmac_f32_e32 v86, v29, v104
	v_fmac_f32_e32 v85, v29, v105
	v_fmac_f32_e32 v84, v29, v106
	v_fmac_f32_e32 v82, v29, v107
	s_waitcnt lgkmcnt(1)
	v_fmac_f32_e32 v97, v29, v108
	v_fmac_f32_e32 v95, v29, v109
	v_fmac_f32_e32 v94, v29, v110
	v_fmac_f32_e32 v93, v29, v111
	s_waitcnt lgkmcnt(0)
	v_fmac_f32_e32 v89, v29, v112
	v_fmac_f32_e32 v88, v29, v113
	v_fmac_f32_e32 v87, v29, v114
	v_fmac_f32_e32 v83, v29, v115
	ds_read_b128 v[28:31], v71
	ds_read_b128 v[100:103], v71 offset:16
	ds_read_b128 v[104:107], v71 offset:32
	ds_read_b128 v[108:111], v71 offset:48
	v_mul_f32_e32 v27, v27, v98
	v_mul_f32_e32 v27, v41, v27
	s_waitcnt lgkmcnt(2)
	v_fmac_f32_e32 v86, v32, v100
	v_fmac_f32_e32 v96, v32, v28
	v_fmac_f32_e32 v92, v32, v29
	v_fmac_f32_e32 v91, v32, v30
	v_fmac_f32_e32 v90, v32, v31
	v_fmac_f32_e32 v85, v32, v101
	v_fmac_f32_e32 v84, v32, v102
	v_fmac_f32_e32 v82, v32, v103
	s_waitcnt lgkmcnt(1)
	v_fmac_f32_e32 v97, v32, v104
	v_fmac_f32_e32 v95, v32, v105
	v_fmac_f32_e32 v94, v32, v106
	v_fmac_f32_e32 v93, v32, v107
	s_waitcnt lgkmcnt(0)
	v_fmac_f32_e32 v89, v32, v108
	v_fmac_f32_e32 v88, v32, v109
	v_fmac_f32_e32 v87, v32, v110
	v_fmac_f32_e32 v83, v32, v111
	v_cvt_pk_bf16_f32 v32, v27, v5
	ds_read_b128 v[28:31], v72
	global_store_short v[0:1], v32, off offset:1024
	ds_read_b128 v[100:103], v72 offset:16
	ds_read_b128 v[104:107], v72 offset:32
	ds_read_b128 v[108:111], v72 offset:48
	v_mul_f32_e32 v26, v26, v98
	v_mul_f32_e32 v25, v25, v98
	s_waitcnt lgkmcnt(3)
	v_fmac_f32_e32 v91, v27, v30
	v_fmac_f32_e32 v90, v27, v31
	v_mul_f32_e32 v30, v42, v26
	v_cvt_pk_bf16_f32 v31, v30, v5
	global_store_short v[0:1], v31, off offset:1152
	v_fmac_f32_e32 v96, v27, v28
	v_fmac_f32_e32 v92, v27, v29
	s_waitcnt lgkmcnt(2)
	v_fmac_f32_e32 v86, v27, v100
	v_fmac_f32_e32 v85, v27, v101
	v_fmac_f32_e32 v84, v27, v102
	v_fmac_f32_e32 v82, v27, v103
	s_waitcnt lgkmcnt(1)
	v_fmac_f32_e32 v97, v27, v104
	v_fmac_f32_e32 v95, v27, v105
	v_fmac_f32_e32 v94, v27, v106
	v_fmac_f32_e32 v93, v27, v107
	s_waitcnt lgkmcnt(0)
	v_fmac_f32_e32 v89, v27, v108
	v_fmac_f32_e32 v88, v27, v109
	v_fmac_f32_e32 v87, v27, v110
	v_fmac_f32_e32 v83, v27, v111
	ds_read_b128 v[26:29], v73
	ds_read_b128 v[100:103], v73 offset:16
	ds_read_b128 v[104:107], v73 offset:32
	ds_read_b128 v[108:111], v73 offset:48
	v_mul_f32_e32 v25, v43, v25
	v_mul_f32_e32 v24, v24, v98
	s_waitcnt lgkmcnt(2)
	v_fmac_f32_e32 v86, v30, v100
	v_fmac_f32_e32 v96, v30, v26
	v_fmac_f32_e32 v92, v30, v27
	v_fmac_f32_e32 v91, v30, v28
	v_fmac_f32_e32 v90, v30, v29
	v_fmac_f32_e32 v85, v30, v101
	v_fmac_f32_e32 v84, v30, v102
	v_fmac_f32_e32 v82, v30, v103
	s_waitcnt lgkmcnt(1)
	v_fmac_f32_e32 v97, v30, v104
	v_fmac_f32_e32 v95, v30, v105
	v_fmac_f32_e32 v94, v30, v106
	v_fmac_f32_e32 v93, v30, v107
	s_waitcnt lgkmcnt(0)
	v_fmac_f32_e32 v89, v30, v108
	v_fmac_f32_e32 v88, v30, v109
	v_fmac_f32_e32 v87, v30, v110
	v_fmac_f32_e32 v83, v30, v111
	v_cvt_pk_bf16_f32 v30, v25, v5
	global_store_short v[0:1], v30, off offset:1280
	ds_read_b128 v[26:29], v74
	ds_read_b128 v[100:103], v74 offset:16
	ds_read_b128 v[104:107], v74 offset:32
	ds_read_b128 v[108:111], v74 offset:48
	v_mul_f32_e32 v32, v44, v24
	v_mul_f32_e32 v23, v23, v98
	s_waitcnt lgkmcnt(2)
	v_fmac_f32_e32 v86, v25, v100
	v_fmac_f32_e32 v96, v25, v26
	v_fmac_f32_e32 v92, v25, v27
	v_fmac_f32_e32 v91, v25, v28
	v_fmac_f32_e32 v90, v25, v29
	v_fmac_f32_e32 v85, v25, v101
	v_fmac_f32_e32 v84, v25, v102
	v_fmac_f32_e32 v82, v25, v103
	s_waitcnt lgkmcnt(1)
; #define LAS __attribute__((address_space(3)))
; __device__ __forceinline__ unsigned cvt_pk_bf16(float lo, float hi) { unsigned r; asm volatile("v_cvt_pk_bf16_f32 %0, %1, %2" : "=v"(r) : "v"(lo), "v"(hi)); return r; }
; __device__ __forceinline__ void p0_phase(const Args& a, LAS unsigned char* lds, int tid, int lane, int wave) {
;     ...
;                 for (int j = 0; j < 16; ++j) { const float xn = xa[u][j] * rstd * gm[j];
;                     XN[(size_t)row * D + lane + 64 * j] = (bf16_t)(cvt_pk_bf16(xn, 0.f) & 0xffffu);
;                     const LAS f32x4* wp = (const LAS f32x4*)(wfl + (lane + 64 * j) * 16);
; #pragma unroll
;                     for (int q = 0; q < 4; ++q) { const f32x4 w = wp[q]; f[4 * q + 0] += xn * w[0]; f[4 * q + 1] += xn * w[1]; f[4 * q + 2] += xn * w[2]; f[4 * q + 3] += xn * w[3]; } }
;                 { const bool b5 = lane & 32;
; #pragma unroll
;                   for (int k = 0; k < 8; ++k) { const float send = b5 ? f[k] : f[k + 8], keep = b5 ? f[k + 8] : f[k]; f[k] = keep + __shfl_xor(send, 32); }
	v_fmac_f32_e32 v97, v25, v104
	v_fmac_f32_e32 v95, v25, v105
	v_fmac_f32_e32 v94, v25, v106
	v_fmac_f32_e32 v93, v25, v107
	s_waitcnt lgkmcnt(0)
	v_fmac_f32_e32 v89, v25, v108
	v_fmac_f32_e32 v88, v25, v109
	v_fmac_f32_e32 v87, v25, v110
	v_fmac_f32_e32 v83, v25, v111
	v_cvt_pk_bf16_f32 v28, v32, v5
	ds_read_b128 v[24:27], v75
	global_store_short v[0:1], v28, off offset:1408
	ds_read_b128 v[28:31], v75 offset:16
	ds_read_b128 v[100:103], v75 offset:32
	ds_read_b128 v[104:107], v75 offset:48
	v_mul_f32_e32 v23, v45, v23
	v_mul_f32_e32 v22, v22, v98
	s_waitcnt lgkmcnt(3)
	v_fmac_f32_e32 v96, v32, v24
	v_fmac_f32_e32 v92, v32, v25
	v_fmac_f32_e32 v91, v32, v26
	v_fmac_f32_e32 v90, v32, v27
	s_waitcnt lgkmcnt(2)
	v_fmac_f32_e32 v86, v32, v28
	v_cvt_pk_bf16_f32 v28, v23, v5
	ds_read_b128 v[24:27], v76
	global_store_short v[0:1], v28, off offset:1536
	v_fmac_f32_e32 v85, v32, v29
	v_fmac_f32_e32 v84, v32, v30
	v_fmac_f32_e32 v82, v32, v31
	s_waitcnt lgkmcnt(2)
	v_fmac_f32_e32 v97, v32, v100
	v_fmac_f32_e32 v95, v32, v101
	v_fmac_f32_e32 v94, v32, v102
	v_fmac_f32_e32 v93, v32, v103
	s_waitcnt lgkmcnt(1)
	v_fmac_f32_e32 v89, v32, v104
	v_fmac_f32_e32 v88, v32, v105
	v_fmac_f32_e32 v87, v32, v106
	v_fmac_f32_e32 v83, v32, v107
	ds_read_b128 v[28:31], v76 offset:16
	ds_read_b128 v[100:103], v76 offset:32
	ds_read_b128 v[104:107], v76 offset:48
	s_waitcnt lgkmcnt(3)
	v_fmac_f32_e32 v91, v23, v26
	v_fmac_f32_e32 v96, v23, v24
	s_waitcnt lgkmcnt(2)
	v_fmac_f32_e32 v84, v23, v30
	v_mul_f32_e32 v30, v46, v22
	v_cvt_pk_bf16_f32 v26, v30, v5
	global_store_short v[0:1], v26, off offset:1664
	v_fmac_f32_e32 v92, v23, v25
	v_fmac_f32_e32 v90, v23, v27
	v_fmac_f32_e32 v86, v23, v28
	v_fmac_f32_e32 v85, v23, v29
	v_fmac_f32_e32 v82, v23, v31
	s_waitcnt lgkmcnt(1)
	v_fmac_f32_e32 v97, v23, v100
	v_fmac_f32_e32 v95, v23, v101
	v_fmac_f32_e32 v94, v23, v102
	v_fmac_f32_e32 v93, v23, v103
	s_waitcnt lgkmcnt(0)
	v_fmac_f32_e32 v89, v23, v104
	v_fmac_f32_e32 v88, v23, v105
	v_fmac_f32_e32 v87, v23, v106
	v_fmac_f32_e32 v83, v23, v107
	ds_read_b128 v[22:25], v77
	ds_read_b128 v[26:29], v77 offset:16
	ds_read_b128 v[100:103], v77 offset:32
	ds_read_b128 v[104:107], v77 offset:48
	v_mul_f32_e32 v21, v21, v98
	v_mul_f32_e32 v20, v20, v98
	s_waitcnt lgkmcnt(2)
	v_fmac_f32_e32 v86, v30, v26
	v_fmac_f32_e32 v96, v30, v22
	v_fmac_f32_e32 v92, v30, v23
	v_fmac_f32_e32 v91, v30, v24
	v_fmac_f32_e32 v90, v30, v25
	v_fmac_f32_e32 v85, v30, v27
	v_fmac_f32_e32 v84, v30, v28
	v_fmac_f32_e32 v82, v30, v29
	s_waitcnt lgkmcnt(1)
	v_fmac_f32_e32 v97, v30, v100
	v_fmac_f32_e32 v95, v30, v101
	v_fmac_f32_e32 v94, v30, v102
	v_fmac_f32_e32 v93, v30, v103
	s_waitcnt lgkmcnt(0)
	v_fmac_f32_e32 v89, v30, v104
	v_fmac_f32_e32 v88, v30, v105
	v_fmac_f32_e32 v87, v30, v106
	v_fmac_f32_e32 v83, v30, v107
	v_mul_f32_e32 v30, v47, v21
	v_cvt_pk_bf16_f32 v21, v30, v5
	ds_read_b128 v[22:25], v78
	global_store_short v[0:1], v21, off offset:1792
	ds_read_b128 v[26:29], v78 offset:16
	ds_read_b128 v[100:103], v78 offset:32
	ds_read_b128 v[104:107], v78 offset:48
	v_mul_f32_e32 v32, v48, v20
	v_cvt_pk_bf16_f32 v80, v32, v5
	s_waitcnt lgkmcnt(3)
	v_fmac_f32_e32 v96, v30, v22
	v_fmac_f32_e32 v92, v30, v23
	ds_read_b128 v[20:23], v79
	v_fmac_f32_e32 v91, v30, v24
	v_fmac_f32_e32 v90, v30, v25
	s_waitcnt lgkmcnt(3)
	v_fmac_f32_e32 v86, v30, v26
	v_fmac_f32_e32 v85, v30, v27
	v_fmac_f32_e32 v84, v30, v28
	v_fmac_f32_e32 v82, v30, v29
	s_waitcnt lgkmcnt(2)
	v_fmac_f32_e32 v97, v30, v100
	v_fmac_f32_e32 v95, v30, v101
	v_fmac_f32_e32 v94, v30, v102
	v_fmac_f32_e32 v93, v30, v103
	s_waitcnt lgkmcnt(1)
	v_fmac_f32_e32 v89, v30, v104
	v_fmac_f32_e32 v88, v30, v105
	v_fmac_f32_e32 v87, v30, v106
	v_fmac_f32_e32 v83, v30, v107
	ds_read_b128 v[24:27], v79 offset:16
	ds_read_b128 v[28:31], v79 offset:32
	ds_read_b128 v[98:101], v79 offset:48
	s_waitcnt lgkmcnt(3)
	v_fmac_f32_e32 v96, v32, v20
	v_fmac_f32_e32 v92, v32, v21
	v_fmac_f32_e32 v91, v32, v22
	s_waitcnt lgkmcnt(1)
	v_fmac_f32_e32 v97, v32, v28
	v_fmac_f32_e32 v95, v32, v29
	v_cndmask_b32_e64 v20, v96, v97, s[26:27]
	v_fmac_f32_e32 v94, v32, v30
	v_mov_b32_e32 v253, v20
	s_nop 1
	v_permlane32_swap_b32_e32 v20, v253
	v_cndmask_b32_e64 v20, v20, v253, s[26:27]
	v_cndmask_b32_e64 v22, v92, v95, s[26:27]
	v_fmac_f32_e32 v90, v32, v23
	v_mov_b32_e32 v253, v22
	s_nop 1
	v_permlane32_swap_b32_e32 v22, v253
	v_cndmask_b32_e64 v22, v22, v253, s[26:27]
	v_cndmask_b32_e64 v23, v91, v94, s[26:27]
	v_mov_b32_e32 v253, v23
	s_nop 1
	v_permlane32_swap_b32_e32 v23, v253
	v_cndmask_b32_e64 v23, v23, v253, s[26:27]
	v_cndmask_b32_e64 v21, v97, v96, s[26:27]
	s_waitcnt lgkmcnt(0)
	v_add_f32_e32 v20, v21, v20
	v_cndmask_b32_e64 v21, v95, v92, s[26:27]
	v_fmac_f32_e32 v93, v32, v31
	s_waitcnt lgkmcnt(0)
	v_add_f32_e32 v21, v21, v22
	v_cndmask_b32_e64 v22, v94, v91, s[26:27]
	v_fmac_f32_e32 v86, v32, v24
	v_fmac_f32_e32 v89, v32, v98
	s_waitcnt lgkmcnt(0)
	v_add_f32_e32 v22, v22, v23
	v_cndmask_b32_e64 v23, v90, v93, s[26:27]
	v_fmac_f32_e32 v85, v32, v25
	v_fmac_f32_e32 v88, v32, v99
	v_mov_b32_e32 v253, v23
	s_nop 1
	v_permlane32_swap_b32_e32 v23, v253
	v_cndmask_b32_e64 v23, v23, v253, s[26:27]
	v_cndmask_b32_e64 v25, v86, v89, s[26:27]
	v_fmac_f32_e32 v84, v32, v26
	v_mov_b32_e32 v253, v25
	s_nop 1
	v_permlane32_swap_b32_e32 v25, v253
	v_cndmask_b32_e64 v25, v25, v253, s[26:27]
	v_cndmask_b32_e64 v26, v85, v88, s[26:27]
	v_mov_b32_e32 v253, v26
	s_nop 1
	v_permlane32_swap_b32_e32 v26, v253
	v_cndmask_b32_e64 v26, v26, v253, s[26:27]
	v_cndmask_b32_e64 v24, v93, v90, s[26:27]
	s_waitcnt lgkmcnt(0)
	v_add_f32_e32 v23, v24, v23
	v_cndmask_b32_e64 v24, v89, v86, s[26:27]
	v_fmac_f32_e32 v87, v32, v100
	s_waitcnt lgkmcnt(0)
; __device__ __forceinline__ void p0_phase(const Args& a, LAS unsigned char* lds, int tid, int lane, int wave) {
;     ...
;                 { const bool b5 = lane & 32;
; #pragma unroll
;                   for (int k = 0; k < 8; ++k) { const float send = b5 ? f[k] : f[k + 8], keep = b5 ? f[k + 8] : f[k]; f[k] = keep + __shfl_xor(send, 32); }
;                   const bool b4 = lane & 16;
; #pragma unroll
;                   for (int k = 0; k < 4; ++k) { const float send = b4 ? f[k] : f[k + 4], keep = b4 ? f[k + 4] : f[k]; f[k] = keep + __shfl_xor(send, 16); }
;                   const bool b3 = lane & 8;
; #pragma unroll
;                   for (int k = 0; k < 2; ++k) { const float send = b3 ? f[k] : f[k + 2], keep = b3 ? f[k + 2] : f[k]; f[k] = keep + __shfl_xor(send, 8); }
;                   const bool b2 = lane & 4;
;                   { const float send = b2 ? f[0] : f[1], keep = b2 ? f[1] : f[0]; f[0] = keep + __shfl_xor(send, 4); }
;                   f[0] += __shfl_xor(f[0], 2); f[0] += __shfl_xor(f[0], 1); }
;                 if ((lane & 3) == 0) { const int hh = ((lane >> 5) & 1) * 8 + ((lane >> 4) & 1) * 4 + ((lane >> 3) & 1) * 2 + ((lane >> 2) & 1);
;                     const float z = f[0] + bfg[hh]; const float lg = fminf(z, 0.f) - log1pf(expf(-fabsf(z)));
;                     lf[rl * 16 + hh] = lg;
;                     if (row < MP) a.out[O_LFP + (size_t)row * NH + hh] = lg; else a.out[O_LFS + (size_t)(row - MP) * NH + hh] = lg; }
	v_add_f32_e32 v24, v24, v25
	v_cndmask_b32_e64 v25, v88, v85, s[26:27]
	v_fmac_f32_e32 v82, v32, v27
	v_fmac_f32_e32 v83, v32, v101
	s_waitcnt lgkmcnt(0)
	v_add_f32_e32 v25, v25, v26
	v_cndmask_b32_e64 v26, v84, v87, s[26:27]
	v_mov_b32_e32 v253, v26
	s_nop 1
	v_permlane32_swap_b32_e32 v26, v253
	v_cndmask_b32_e64 v26, v26, v253, s[26:27]
	v_cndmask_b32_e64 v28, v82, v83, s[26:27]
	v_mov_b32_e32 v253, v28
	s_nop 1
	v_permlane32_swap_b32_e32 v28, v253
	v_cndmask_b32_e64 v28, v28, v253, s[26:27]
	v_cndmask_b32_e64 v27, v87, v84, s[26:27]
	v_cndmask_b32_e64 v29, v20, v24, s[28:29]
	s_waitcnt lgkmcnt(0)
	v_add_f32_e32 v26, v27, v26
	v_cndmask_b32_e64 v27, v83, v82, s[26:27]
	s_waitcnt lgkmcnt(0)
	v_add_f32_e32 v27, v27, v28
	v_cndmask_b32_e64 v20, v24, v20, s[28:29]
	v_cndmask_b32_e64 v24, v21, v25, s[28:29]
	v_cndmask_b32_e64 v21, v25, v21, s[28:29]
	v_cndmask_b32_e64 v25, v22, v26, s[28:29]
	v_cndmask_b32_e64 v28, v23, v27, s[28:29]
	v_mov_b32_e32 v253, v29
	s_nop 1
	v_permlane16_swap_b32_e32 v29, v253
	v_cndmask_b32_e64 v29, v29, v253, s[28:29]
	v_mov_b32_e32 v253, v24
	s_nop 1
	v_permlane16_swap_b32_e32 v24, v253
	v_cndmask_b32_e64 v24, v24, v253, s[28:29]
	v_mov_b32_e32 v253, v25
	s_nop 1
	v_permlane16_swap_b32_e32 v25, v253
	v_cndmask_b32_e64 v25, v25, v253, s[28:29]
	v_mov_b32_e32 v253, v28
	s_nop 1
	v_permlane16_swap_b32_e32 v28, v253
	v_cndmask_b32_e64 v28, v28, v253, s[28:29]
	v_cndmask_b32_e64 v22, v26, v22, s[28:29]
	v_cndmask_b32_e64 v23, v27, v23, s[28:29]
	s_waitcnt lgkmcnt(0)
	v_add_f32_e32 v20, v20, v29
	s_waitcnt lgkmcnt(0)
	v_add_f32_e32 v21, v21, v24
	s_waitcnt lgkmcnt(0)
	v_add_f32_e32 v22, v22, v25
	s_waitcnt lgkmcnt(0)
	v_add_f32_e32 v23, v23, v28
	v_cndmask_b32_e64 v24, v20, v22, s[30:31]
	v_cndmask_b32_e64 v25, v21, v23, s[30:31]
	s_nop 1
	v_mov_b32_dpp v24, v24 row_ror:8 row_mask:0xf bank_mask:0xf
	s_nop 1
	v_mov_b32_dpp v25, v25 row_ror:8 row_mask:0xf bank_mask:0xf
	v_cndmask_b32_e64 v20, v22, v20, s[30:31]
	v_cndmask_b32_e64 v21, v23, v21, s[30:31]
	global_store_short v[0:1], v80, off offset:1920
	s_waitcnt lgkmcnt(0)
	v_add_f32_e32 v20, v20, v24
	s_waitcnt lgkmcnt(0)
	v_add_f32_e32 v21, v21, v25
	v_cndmask_b32_e64 v22, v20, v21, s[34:35]
	v_mov_b32_e32 v253, v22
	s_nop 1
	v_mov_b32_dpp v22, v253 row_shl:4 row_mask:0xf bank_mask:0x5
	s_nop 1
	v_mov_b32_dpp v22, v253 row_shr:4 row_mask:0xf bank_mask:0xa
	v_cndmask_b32_e64 v20, v21, v20, s[34:35]
	s_waitcnt lgkmcnt(0)
	v_add_f32_e32 v20, v20, v22
	s_nop 1
	v_mov_b32_dpp v21, v20 quad_perm:[2,3,0,1] row_mask:0xf bank_mask:0xf
	s_waitcnt lgkmcnt(0)
	v_add_f32_e32 v20, v20, v21
	s_nop 1
	v_mov_b32_dpp v21, v20 quad_perm:[1,0,3,2] row_mask:0xf bank_mask:0xf
	s_and_saveexec_b64 s[0:1], s[36:37]
	s_cbranch_execz .LBB0_32
	global_load_dword v0, v[10:11], off
	s_waitcnt lgkmcnt(0)
	v_add_f32_e32 v1, v20, v21
	v_lshl_add_u32 v20, s10, 6, v51
	s_add_i32 s10, s92, 0xffffc000
	s_cmpk_lt_i32 s92, 0x4000
	s_cselect_b32 s11, s93, 0
	s_cselect_b32 s10, s92, s10
	s_cselect_b32 s12, s7, 0xcd04000
	s_lshl_b64 s[10:11], s[10:11], 6
	s_add_u32 s10, s86, s10
	s_addc_u32 s11, s87, s11
	s_add_u32 s92, s10, s12
	s_addc_u32 s93, s11, 0
	s_waitcnt vmcnt(0)
	v_add_f32_e32 v0, v1, v0
	v_mul_f32_e64 v1, |v0|, s70
	v_fma_f32 v21, |v0|, s70, -v1
	v_rndne_f32_e32 v22, v1
	v_fma_f32 v21, |v0|, s71, v21
	v_sub_f32_e32 v1, v1, v22
	v_add_f32_e32 v1, v1, v21
	v_cvt_i32_f32_e32 v22, v22
	v_exp_f32_e32 v1, v1
	v_cmp_ngt_f32_e64 vcc, |v0|, s50
	v_min_f32_e32 v21, 0, v0
	v_ldexp_f32 v1, v1, v22
	v_cndmask_b32_e32 v1, 0, v1, vcc
	v_cmp_nlt_f32_e64 vcc, |v0|, s94
	s_nop 1
	v_cndmask_b32_e32 v22, v63, v1, vcc
	v_add_f32_e32 v23, 1.0, v22
	v_add_f32_e32 v24, -1.0, v23
	v_frexp_mant_f32_e32 v25, v23
	v_cvt_f64_f32_e32 v[0:1], v23
	v_sub_f32_e32 v26, v24, v23
	v_frexp_exp_i32_f64_e32 v0, v[0:1]
	v_cmp_gt_f32_e32 vcc, s4, v25
	v_sub_f32_e32 v24, v22, v24
	v_add_f32_e32 v1, 1.0, v26
	v_subbrev_co_u32_e32 v0, vcc, 0, v0, vcc
	v_add_f32_e32 v1, v24, v1
	v_sub_u32_e32 v24, 0, v0
	v_cvt_f32_i32_e32 v0, v0
	v_ldexp_f32 v23, v23, v24
	v_ldexp_f32 v1, v1, v24
	v_add_f32_e32 v24, -1.0, v23
	v_add_f32_e32 v25, 1.0, v23
	v_add_f32_e32 v26, 1.0, v24
	v_add_f32_e32 v27, -1.0, v25
	v_sub_f32_e32 v26, v23, v26
	v_sub_f32_e32 v23, v23, v27
	v_mul_f32_e32 v27, 0x3f317218, v0
	v_add_f32_e32 v26, v1, v26
	v_add_f32_e32 v1, v1, v23
	v_fma_f32 v23, v0, s5, -v27
	v_add_f32_e32 v28, v24, v26
	v_add_f32_e32 v29, v25, v1
	v_fmac_f32_e32 v23, 0xb102e308, v0
	v_sub_f32_e32 v0, v24, v28
	v_sub_f32_e32 v24, v25, v29
	v_rcp_f32_e32 v25, v29
	v_add_f32_e32 v30, v27, v23
	v_add_f32_e32 v1, v1, v24
	v_sub_f32_e32 v24, v30, v27
	v_sub_f32_e32 v23, v23, v24
	v_mul_f32_e32 v24, v28, v25
	v_add_f32_e32 v0, v26, v0
	v_mul_f32_e32 v26, v29, v24
	v_fma_f32 v27, v24, v29, -v26
	v_fmac_f32_e32 v27, v24, v1
	v_add_f32_e32 v31, v26, v27
	v_sub_f32_e32 v32, v28, v31
	v_sub_f32_e32 v26, v31, v26
	v_sub_f32_e32 v28, v28, v32
	v_sub_f32_e32 v26, v26, v27
	v_sub_f32_e32 v27, v28, v31
	v_add_f32_e32 v0, v0, v27
	v_add_f32_e32 v0, v26, v0
	v_add_f32_e32 v26, v32, v0
	v_mul_f32_e32 v27, v25, v26
	v_sub_f32_e32 v28, v32, v26
	v_mul_f32_e32 v31, v29, v27
	v_add_f32_e32 v0, v0, v28
	v_add_f32_e32 v28, v24, v27
	v_fma_f32 v29, v27, v29, -v31
	v_sub_f32_e32 v24, v28, v24
	v_fmac_f32_e32 v29, v27, v1
	v_sub_f32_e32 v1, v27, v24
	v_add_f32_e32 v24, v31, v29
	v_sub_f32_e32 v27, v24, v31
	v_sub_f32_e32 v31, v26, v24
	v_sub_f32_e32 v26, v26, v31
	v_sub_f32_e32 v24, v26, v24
	v_sub_f32_e32 v27, v27, v29
	v_add_f32_e32 v0, v0, v24
	v_add_f32_e32 v0, v27, v0
	v_add_f32_e32 v0, v31, v0
	v_mul_f32_e32 v0, v25, v0
	v_add_f32_e32 v0, v1, v0
	v_add_f32_e32 v1, v28, v0
	v_mul_f32_e32 v24, v1, v1
	v_fmamk_f32 v27, v24, 0x3e9b6dac, v62
	v_sub_f32_e32 v25, v1, v28
	v_ldexp_f32 v26, v1, 1
	v_mul_f32_e32 v1, v1, v24
	v_fmaak_f32 v24, v24, v27, 0x3f2aaada
	v_mul_f32_e32 v1, v1, v24
	v_add_f32_e32 v24, v26, v1
	v_sub_f32_e32 v0, v0, v25
	v_sub_f32_e32 v25, v24, v26
	v_ldexp_f32 v0, v0, 1
	v_sub_f32_e32 v1, v1, v25
	v_add_f32_e32 v0, v0, v1
	v_add_f32_e32 v1, v24, v0
	v_sub_f32_e32 v24, v1, v24
	v_add_f32_e32 v25, v30, v1
	v_sub_f32_e32 v0, v0, v24
	v_sub_f32_e32 v24, v25, v30
	v_sub_f32_e32 v26, v25, v24
	v_sub_f32_e32 v1, v1, v24
	v_add_f32_e32 v24, v23, v0
	v_sub_f32_e32 v26, v30, v26
	v_sub_f32_e32 v27, v24, v23
	v_add_f32_e32 v1, v1, v26
	v_sub_f32_e32 v26, v24, v27
	v_sub_f32_e32 v0, v0, v27
	v_sub_f32_e32 v23, v23, v26
	v_add_f32_e32 v1, v24, v1
	v_add_f32_e32 v0, v0, v23
	v_add_f32_e32 v23, v25, v1
	v_sub_f32_e32 v24, v23, v25
	v_sub_f32_e32 v1, v1, v24
	v_add_f32_e32 v0, v0, v1
	v_add_f32_e32 v0, v23, v0
	v_cmp_neq_f32_e32 vcc, s95, v22
	s_nop 1
	v_cndmask_b32_e32 v0, v63, v0, vcc
	v_cmp_lt_f32_e64 vcc, |v22|, s6
	s_nop 1
	v_cndmask_b32_e32 v0, v0, v22, vcc
	v_sub_f32_e32 v0, v21, v0
	ds_write_b32 v20, v0
	global_store_dword v33, v0, s[92:93]
	s_branch .LBB0_32
